# v14 + loop-edge: K-loop counter updates and exit test hoisted above the loop-back barrier
# baseline (speedup 1.0000x reference)
.LBB0_121:
	ds_read_b128 v[164:167], v131
	ds_read_b128 v[168:171], v131 offset:1024
	ds_read_b128 v[172:175], v131 offset:2048
	ds_read_b128 v[176:179], v131 offset:3072
	ds_read_b128 v[180:183], v160
	ds_read_b128 v[184:187], v160 offset:1024
	ds_read_b128 v[188:191], v160 offset:2048
	ds_read_b128 v[192:195], v160 offset:3072
	s_add_i32 s55, s52, 0xfffc0080
	s_cmp_eq_u32 s54, 12
	s_cselect_b32 s57, s16, s55
	s_cselect_b32 s56, s17, s53
	s_or_b32 s55, s57, 0x80
	s_mov_b32 m0, s40
	s_nop 0
	buffer_load_dwordx4 v156, s[12:15], s52 offen lds
	s_nop 0
	s_mov_b32 m0, s41
	s_nop 0
	buffer_load_dwordx4 v157, s[12:15], s52 offen lds
	ds_read_b128 v[196:199], v161
	ds_read_b128 v[200:203], v161 offset:1024
	ds_read_b128 v[204:207], v161 offset:2048
	ds_read_b128 v[208:211], v161 offset:3072
	ds_read_b128 v[212:215], v161 offset:4096
	ds_read_b128 v[216:219], v161 offset:5120
	ds_read_b128 v[220:223], v161 offset:6144
	ds_read_b128 v[224:227], v161 offset:7168
	s_waitcnt vmcnt(8)
	s_waitcnt lgkmcnt(0)
	s_barrier
	s_setprio 1
	s_waitcnt lgkmcnt(7)
	v_mfma_f32_16x16x32_bf16 v[126:129], v[164:167], v[196:199], v[126:129]
	v_mfma_f32_16x16x32_bf16 v[122:125], v[172:175], v[196:199], v[122:125]
	s_waitcnt lgkmcnt(5)
	v_mfma_f32_16x16x32_bf16 v[118:121], v[164:167], v[204:207], v[118:121]
	v_mfma_f32_16x16x32_bf16 v[110:113], v[172:175], v[204:207], v[110:113]
	s_waitcnt lgkmcnt(3)
	v_mfma_f32_16x16x32_bf16 v[102:105], v[164:167], v[212:215], v[102:105]
	v_mfma_f32_16x16x32_bf16 v[94:97], v[172:175], v[212:215], v[94:97]
	s_waitcnt lgkmcnt(1)
	v_mfma_f32_16x16x32_bf16 v[86:89], v[164:167], v[220:223], v[86:89]
	v_mfma_f32_16x16x32_bf16 v[78:81], v[172:175], v[220:223], v[78:81]
	v_mfma_f32_16x16x32_bf16 v[126:129], v[168:171], v[200:203], v[126:129]
	v_mfma_f32_16x16x32_bf16 v[122:125], v[176:179], v[200:203], v[122:125]
	v_mfma_f32_16x16x32_bf16 v[118:121], v[168:171], v[208:211], v[118:121]
	v_mfma_f32_16x16x32_bf16 v[110:113], v[176:179], v[208:211], v[110:113]
	v_mfma_f32_16x16x32_bf16 v[102:105], v[168:171], v[216:219], v[102:105]
	v_mfma_f32_16x16x32_bf16 v[94:97], v[176:179], v[216:219], v[94:97]
	s_waitcnt lgkmcnt(0)
	v_mfma_f32_16x16x32_bf16 v[86:89], v[168:171], v[224:227], v[86:89]
	v_mfma_f32_16x16x32_bf16 v[78:81], v[176:179], v[224:227], v[78:81]
	s_setprio 0
	s_setprio 1
	v_mfma_f32_16x16x32_bf16 v[114:117], v[180:183], v[196:199], v[114:117]
	v_mfma_f32_16x16x32_bf16 v[106:109], v[188:191], v[196:199], v[106:109]
	v_mfma_f32_16x16x32_bf16 v[98:101], v[180:183], v[204:207], v[98:101]
	v_mfma_f32_16x16x32_bf16 v[90:93], v[188:191], v[204:207], v[90:93]
	v_mfma_f32_16x16x32_bf16 v[82:85], v[180:183], v[212:215], v[82:85]
	v_mfma_f32_16x16x32_bf16 v[74:77], v[188:191], v[212:215], v[74:77]
	v_mfma_f32_16x16x32_bf16 v[70:73], v[180:183], v[220:223], v[70:73]
	v_mfma_f32_16x16x32_bf16 v[66:69], v[188:191], v[220:223], v[66:69]
	v_mfma_f32_16x16x32_bf16 v[114:117], v[184:187], v[200:203], v[114:117]
	v_mfma_f32_16x16x32_bf16 v[106:109], v[192:195], v[200:203], v[106:109]
	v_mfma_f32_16x16x32_bf16 v[98:101], v[184:187], v[208:211], v[98:101]
	v_mfma_f32_16x16x32_bf16 v[90:93], v[192:195], v[208:211], v[90:93]
	v_mfma_f32_16x16x32_bf16 v[82:85], v[184:187], v[216:219], v[82:85]
	v_mfma_f32_16x16x32_bf16 v[74:77], v[192:195], v[216:219], v[74:77]
	v_mfma_f32_16x16x32_bf16 v[70:73], v[184:187], v[224:227], v[70:73]
	v_mfma_f32_16x16x32_bf16 v[66:69], v[192:195], v[224:227], v[66:69]
	s_setprio 0
	s_barrier
	ds_read_b128 v[196:199], v161 offset:16384
	ds_read_b128 v[200:203], v161 offset:17408
	s_mov_b32 m0, s22
	s_nop 0
	buffer_load_dwordx4 v154, s[8:11], s56 offen lds
	ds_read_b128 v[204:207], v161 offset:18432
	ds_read_b128 v[208:211], v161 offset:19456
	s_add_i32 s58, s56, 0x40000
	s_mov_b32 m0, s23
	s_nop 0
	buffer_load_dwordx4 v155, s[8:11], s56 offen lds
	ds_read_b128 v[212:215], v161 offset:20480
	ds_read_b128 v[216:219], v161 offset:21504
	s_nop 0
	s_mov_b32 m0, s24
	s_nop 0
	buffer_load_dwordx4 v154, s[8:11], s58 offen lds
	ds_read_b128 v[220:223], v161 offset:22528
	ds_read_b128 v[224:227], v161 offset:23552
	s_nop 0
	s_mov_b32 m0, s25
	s_nop 0
	buffer_load_dwordx4 v155, s[8:11], s58 offen lds
	s_nop 0
	s_mov_b32 m0, s21
	s_nop 0
	buffer_load_dwordx4 v156, s[12:15], s57 offen lds
	s_nop 0
	s_mov_b32 m0, s27
	s_nop 0
	buffer_load_dwordx4 v157, s[12:15], s57 offen lds
	s_waitcnt vmcnt(8)
	s_waitcnt lgkmcnt(0)
	s_barrier
	s_setprio 1
	s_waitcnt lgkmcnt(7)
	v_mfma_f32_16x16x32_bf16 v[62:65], v[164:167], v[196:199], v[62:65]
	v_mfma_f32_16x16x32_bf16 v[58:61], v[172:175], v[196:199], v[58:61]
	s_waitcnt lgkmcnt(5)
	v_mfma_f32_16x16x32_bf16 v[54:57], v[164:167], v[204:207], v[54:57]
	v_mfma_f32_16x16x32_bf16 v[46:49], v[172:175], v[204:207], v[46:49]
	s_waitcnt lgkmcnt(3)
	v_mfma_f32_16x16x32_bf16 v[38:41], v[164:167], v[212:215], v[38:41]
	v_mfma_f32_16x16x32_bf16 v[30:33], v[172:175], v[212:215], v[30:33]
	s_waitcnt lgkmcnt(1)
	v_mfma_f32_16x16x32_bf16 v[22:25], v[164:167], v[220:223], v[22:25]
	v_mfma_f32_16x16x32_bf16 v[14:17], v[172:175], v[220:223], v[14:17]
	v_mfma_f32_16x16x32_bf16 v[62:65], v[168:171], v[200:203], v[62:65]
	v_mfma_f32_16x16x32_bf16 v[58:61], v[176:179], v[200:203], v[58:61]
	v_mfma_f32_16x16x32_bf16 v[54:57], v[168:171], v[208:211], v[54:57]
	v_mfma_f32_16x16x32_bf16 v[46:49], v[176:179], v[208:211], v[46:49]
	v_mfma_f32_16x16x32_bf16 v[38:41], v[168:171], v[216:219], v[38:41]
	v_mfma_f32_16x16x32_bf16 v[30:33], v[176:179], v[216:219], v[30:33]
	s_waitcnt lgkmcnt(0)
	v_mfma_f32_16x16x32_bf16 v[22:25], v[168:171], v[224:227], v[22:25]
	v_mfma_f32_16x16x32_bf16 v[14:17], v[176:179], v[224:227], v[14:17]
	s_setprio 0
	s_setprio 1
	v_mfma_f32_16x16x32_bf16 v[50:53], v[180:183], v[196:199], v[50:53]
	v_mfma_f32_16x16x32_bf16 v[42:45], v[188:191], v[196:199], v[42:45]
	v_mfma_f32_16x16x32_bf16 v[34:37], v[180:183], v[204:207], v[34:37]
	v_mfma_f32_16x16x32_bf16 v[26:29], v[188:191], v[204:207], v[26:29]
	v_mfma_f32_16x16x32_bf16 v[18:21], v[180:183], v[212:215], v[18:21]
	v_mfma_f32_16x16x32_bf16 v[10:13], v[188:191], v[212:215], v[10:13]
	v_mfma_f32_16x16x32_bf16 v[6:9], v[180:183], v[220:223], v[6:9]
	v_mfma_f32_16x16x32_bf16 v[2:5], v[188:191], v[220:223], v[2:5]
	v_mfma_f32_16x16x32_bf16 v[50:53], v[184:187], v[200:203], v[50:53]
	v_mfma_f32_16x16x32_bf16 v[42:45], v[192:195], v[200:203], v[42:45]
	v_mfma_f32_16x16x32_bf16 v[34:37], v[184:187], v[208:211], v[34:37]
	v_mfma_f32_16x16x32_bf16 v[26:29], v[192:195], v[208:211], v[26:29]
	v_mfma_f32_16x16x32_bf16 v[18:21], v[184:187], v[216:219], v[18:21]
	v_mfma_f32_16x16x32_bf16 v[10:13], v[192:195], v[216:219], v[10:13]
	v_mfma_f32_16x16x32_bf16 v[6:9], v[184:187], v[224:227], v[6:9]
	v_mfma_f32_16x16x32_bf16 v[2:5], v[192:195], v[224:227], v[2:5]
	s_setprio 0
	s_barrier
	ds_read_b128 v[164:167], v162
	ds_read_b128 v[168:171], v162 offset:1024
	ds_read_b128 v[172:175], v162 offset:2048
	ds_read_b128 v[176:179], v162 offset:3072
	ds_read_b128 v[180:183], v163
	ds_read_b128 v[184:187], v163 offset:1024
	ds_read_b128 v[188:191], v163 offset:2048
	ds_read_b128 v[192:195], v163 offset:3072
	s_add_i32 s57, s57, 0x40000
	s_mov_b32 m0, s28
	s_nop 0
	buffer_load_dwordx4 v156, s[12:15], s57 offen lds
	s_nop 0
	s_mov_b32 m0, s30
	s_nop 0
	buffer_load_dwordx4 v157, s[12:15], s57 offen lds
	ds_read_b128 v[196:199], v161 offset:32768
	ds_read_b128 v[200:203], v161 offset:33792
	ds_read_b128 v[204:207], v161 offset:34816
	ds_read_b128 v[208:211], v161 offset:35840
	ds_read_b128 v[212:215], v161 offset:36864
	ds_read_b128 v[216:219], v161 offset:37888
	ds_read_b128 v[220:223], v161 offset:38912
	ds_read_b128 v[224:227], v161 offset:39936
	s_waitcnt vmcnt(8)
	s_waitcnt lgkmcnt(0)
	s_barrier
	s_setprio 1
	s_waitcnt lgkmcnt(7)
	v_mfma_f32_16x16x32_bf16 v[126:129], v[164:167], v[196:199], v[126:129]
	v_mfma_f32_16x16x32_bf16 v[122:125], v[172:175], v[196:199], v[122:125]
	s_waitcnt lgkmcnt(5)
	v_mfma_f32_16x16x32_bf16 v[118:121], v[164:167], v[204:207], v[118:121]
	v_mfma_f32_16x16x32_bf16 v[110:113], v[172:175], v[204:207], v[110:113]
	s_waitcnt lgkmcnt(3)
	v_mfma_f32_16x16x32_bf16 v[102:105], v[164:167], v[212:215], v[102:105]
	v_mfma_f32_16x16x32_bf16 v[94:97], v[172:175], v[212:215], v[94:97]
	s_waitcnt lgkmcnt(1)
	v_mfma_f32_16x16x32_bf16 v[86:89], v[164:167], v[220:223], v[86:89]
	v_mfma_f32_16x16x32_bf16 v[78:81], v[172:175], v[220:223], v[78:81]
	v_mfma_f32_16x16x32_bf16 v[126:129], v[168:171], v[200:203], v[126:129]
	v_mfma_f32_16x16x32_bf16 v[122:125], v[176:179], v[200:203], v[122:125]
	v_mfma_f32_16x16x32_bf16 v[118:121], v[168:171], v[208:211], v[118:121]
	v_mfma_f32_16x16x32_bf16 v[110:113], v[176:179], v[208:211], v[110:113]
	v_mfma_f32_16x16x32_bf16 v[102:105], v[168:171], v[216:219], v[102:105]
	v_mfma_f32_16x16x32_bf16 v[94:97], v[176:179], v[216:219], v[94:97]
	s_waitcnt lgkmcnt(0)
	v_mfma_f32_16x16x32_bf16 v[86:89], v[168:171], v[224:227], v[86:89]
	v_mfma_f32_16x16x32_bf16 v[78:81], v[176:179], v[224:227], v[78:81]
	s_setprio 0
	s_setprio 1
	v_mfma_f32_16x16x32_bf16 v[114:117], v[180:183], v[196:199], v[114:117]
	v_mfma_f32_16x16x32_bf16 v[106:109], v[188:191], v[196:199], v[106:109]
	v_mfma_f32_16x16x32_bf16 v[98:101], v[180:183], v[204:207], v[98:101]
	v_mfma_f32_16x16x32_bf16 v[90:93], v[188:191], v[204:207], v[90:93]
	v_mfma_f32_16x16x32_bf16 v[82:85], v[180:183], v[212:215], v[82:85]
	v_mfma_f32_16x16x32_bf16 v[74:77], v[188:191], v[212:215], v[74:77]
	v_mfma_f32_16x16x32_bf16 v[70:73], v[180:183], v[220:223], v[70:73]
	v_mfma_f32_16x16x32_bf16 v[66:69], v[188:191], v[220:223], v[66:69]
	v_mfma_f32_16x16x32_bf16 v[114:117], v[184:187], v[200:203], v[114:117]
	v_mfma_f32_16x16x32_bf16 v[106:109], v[192:195], v[200:203], v[106:109]
	v_mfma_f32_16x16x32_bf16 v[98:101], v[184:187], v[208:211], v[98:101]
	v_mfma_f32_16x16x32_bf16 v[90:93], v[192:195], v[208:211], v[90:93]
	v_mfma_f32_16x16x32_bf16 v[82:85], v[184:187], v[216:219], v[82:85]
	v_mfma_f32_16x16x32_bf16 v[74:77], v[192:195], v[216:219], v[74:77]
	v_mfma_f32_16x16x32_bf16 v[70:73], v[184:187], v[224:227], v[70:73]
	v_mfma_f32_16x16x32_bf16 v[66:69], v[192:195], v[224:227], v[66:69]
	s_setprio 0
	s_barrier
	ds_read_b128 v[196:199], v161 offset:49152
	ds_read_b128 v[200:203], v161 offset:50176
	s_or_b32 s57, s56, 0x80
	s_mov_b32 m0, s34
	s_nop 0
	buffer_load_dwordx4 v154, s[8:11], s57 offen lds
	ds_read_b128 v[204:207], v161 offset:51200
	ds_read_b128 v[208:211], v161 offset:52224
	s_add_i32 s56, s56, 0x40080
	s_mov_b32 m0, s35
	s_nop 0
	buffer_load_dwordx4 v155, s[8:11], s57 offen lds
	ds_read_b128 v[212:215], v161 offset:53248
	ds_read_b128 v[216:219], v161 offset:54272
	s_nop 0
	s_mov_b32 m0, s38
	s_nop 0
	buffer_load_dwordx4 v154, s[8:11], s56 offen lds
	ds_read_b128 v[220:223], v161 offset:55296
	ds_read_b128 v[224:227], v161 offset:56320
	s_nop 0
	s_mov_b32 m0, s39
	s_nop 0
	buffer_load_dwordx4 v155, s[8:11], s56 offen lds
	s_nop 0
	s_mov_b32 m0, s36
	s_nop 0
	buffer_load_dwordx4 v156, s[12:15], s55 offen lds
	s_nop 0
	s_mov_b32 m0, s37
	s_nop 0
	buffer_load_dwordx4 v157, s[12:15], s55 offen lds
	s_waitcnt vmcnt(8)
	s_waitcnt lgkmcnt(0)
	s_barrier
	s_setprio 1
	s_waitcnt lgkmcnt(7)
	v_mfma_f32_16x16x32_bf16 v[62:65], v[164:167], v[196:199], v[62:65]
	v_mfma_f32_16x16x32_bf16 v[58:61], v[172:175], v[196:199], v[58:61]
	s_waitcnt lgkmcnt(5)
	v_mfma_f32_16x16x32_bf16 v[54:57], v[164:167], v[204:207], v[54:57]
	v_mfma_f32_16x16x32_bf16 v[46:49], v[172:175], v[204:207], v[46:49]
	s_waitcnt lgkmcnt(3)
	v_mfma_f32_16x16x32_bf16 v[38:41], v[164:167], v[212:215], v[38:41]
	v_mfma_f32_16x16x32_bf16 v[30:33], v[172:175], v[212:215], v[30:33]
	s_waitcnt lgkmcnt(1)
	v_mfma_f32_16x16x32_bf16 v[22:25], v[164:167], v[220:223], v[22:25]
	v_mfma_f32_16x16x32_bf16 v[14:17], v[172:175], v[220:223], v[14:17]
	v_mfma_f32_16x16x32_bf16 v[62:65], v[168:171], v[200:203], v[62:65]
	v_mfma_f32_16x16x32_bf16 v[58:61], v[176:179], v[200:203], v[58:61]
	v_mfma_f32_16x16x32_bf16 v[54:57], v[168:171], v[208:211], v[54:57]
	v_mfma_f32_16x16x32_bf16 v[46:49], v[176:179], v[208:211], v[46:49]
	v_mfma_f32_16x16x32_bf16 v[38:41], v[168:171], v[216:219], v[38:41]
	v_mfma_f32_16x16x32_bf16 v[30:33], v[176:179], v[216:219], v[30:33]
	s_waitcnt lgkmcnt(0)
	v_mfma_f32_16x16x32_bf16 v[22:25], v[168:171], v[224:227], v[22:25]
	v_mfma_f32_16x16x32_bf16 v[14:17], v[176:179], v[224:227], v[14:17]
	s_setprio 0
	s_setprio 1
	v_mfma_f32_16x16x32_bf16 v[50:53], v[180:183], v[196:199], v[50:53]
	v_mfma_f32_16x16x32_bf16 v[42:45], v[188:191], v[196:199], v[42:45]
	v_mfma_f32_16x16x32_bf16 v[34:37], v[180:183], v[204:207], v[34:37]
	v_mfma_f32_16x16x32_bf16 v[26:29], v[188:191], v[204:207], v[26:29]
	v_mfma_f32_16x16x32_bf16 v[18:21], v[180:183], v[212:215], v[18:21]
	v_mfma_f32_16x16x32_bf16 v[10:13], v[188:191], v[212:215], v[10:13]
	v_mfma_f32_16x16x32_bf16 v[6:9], v[180:183], v[220:223], v[6:9]
	v_mfma_f32_16x16x32_bf16 v[2:5], v[188:191], v[220:223], v[2:5]
	v_mfma_f32_16x16x32_bf16 v[50:53], v[184:187], v[200:203], v[50:53]
	v_mfma_f32_16x16x32_bf16 v[42:45], v[192:195], v[200:203], v[42:45]
	v_mfma_f32_16x16x32_bf16 v[34:37], v[184:187], v[208:211], v[34:37]
	v_mfma_f32_16x16x32_bf16 v[26:29], v[192:195], v[208:211], v[26:29]
	v_mfma_f32_16x16x32_bf16 v[18:21], v[184:187], v[216:219], v[18:21]
	v_mfma_f32_16x16x32_bf16 v[10:13], v[192:195], v[216:219], v[10:13]
	v_mfma_f32_16x16x32_bf16 v[6:9], v[184:187], v[224:227], v[6:9]
	v_mfma_f32_16x16x32_bf16 v[2:5], v[192:195], v[224:227], v[2:5]
	s_setprio 0
	s_add_i32 s54, s54, 2
	s_addk_i32 s52, 0x100
	s_addk_i32 s53, 0x100
	s_cmp_gt_u32 s54, 13
	s_barrier
	s_cbranch_scc0 .LBB0_121
	s_and_b64 vcc, exec, s[6:7]
	s_cbranch_vccz .LBB0_126
	s_barrier
	s_cmp_gt_i32 s46, 3
	s_mov_b64 s[16:17], -1
	s_cbranch_scc1 .LBB0_127

.LBB0_223:
	v_add_u32_e32 v150, 0x10000, v132
	v_add_u32_e32 v166, 0x14000, v132
	ds_read_b128 v[134:137], v150
	ds_read_b128 v[142:145], v150 offset:1024
	ds_read_b128 v[146:149], v150 offset:2048
	ds_read_b128 v[150:153], v150 offset:3072
	ds_read_b128 v[154:157], v166
	ds_read_b128 v[158:161], v166 offset:1024
	ds_read_b128 v[162:165], v166 offset:2048
	ds_read_b128 v[166:169], v166 offset:3072
	s_add_i32 s63, s39, s60
	s_add_i32 s62, s34, s60
	s_add_i32 s61, s63, 0x800
	s_addk_i32 s62, 0x800
	s_cmp_eq_u32 s60, 0
	s_cselect_b32 s64, s55, s61
	s_cselect_b32 s62, s58, s62
	s_or_b32 s61, s64, 0x80
	s_add_i32 s63, s63, 0x40780
	s_mov_b32 m0, s49
	s_nop 0
	buffer_load_dwordx4 v130, s[12:15], s63 offen lds
	s_nop 0
	s_mov_b32 m0, s50
	s_nop 0
	buffer_load_dwordx4 v131, s[12:15], s63 offen lds
	ds_read_b128 v[170:173], v133
	ds_read_b128 v[174:177], v133 offset:1024
	ds_read_b128 v[178:181], v133 offset:2048
	ds_read_b128 v[182:185], v133 offset:3072
	ds_read_b128 v[186:189], v133 offset:4096
	ds_read_b128 v[190:193], v133 offset:5120
	ds_read_b128 v[194:197], v133 offset:6144
	ds_read_b128 v[198:201], v133 offset:7168
	s_waitcnt vmcnt(8)
	s_waitcnt lgkmcnt(0)
	s_barrier
	s_setprio 1
	s_waitcnt lgkmcnt(7)
	v_mfma_f32_16x16x32_bf16 v[138:141], v[134:137], v[170:173], v[138:141]
	v_mfma_f32_16x16x32_bf16 v[126:129], v[146:149], v[170:173], v[126:129]
	s_waitcnt lgkmcnt(5)
	v_mfma_f32_16x16x32_bf16 v[110:113], v[134:137], v[178:181], v[110:113]
	v_mfma_f32_16x16x32_bf16 v[106:109], v[146:149], v[178:181], v[106:109]
	s_waitcnt lgkmcnt(3)
	v_mfma_f32_16x16x32_bf16 v[94:97], v[134:137], v[186:189], v[94:97]
	v_mfma_f32_16x16x32_bf16 v[90:93], v[146:149], v[186:189], v[90:93]
	s_waitcnt lgkmcnt(1)
	v_mfma_f32_16x16x32_bf16 v[78:81], v[134:137], v[194:197], v[78:81]
	v_mfma_f32_16x16x32_bf16 v[74:77], v[146:149], v[194:197], v[74:77]
	v_mfma_f32_16x16x32_bf16 v[138:141], v[142:145], v[174:177], v[138:141]
	v_mfma_f32_16x16x32_bf16 v[126:129], v[150:153], v[174:177], v[126:129]
	v_mfma_f32_16x16x32_bf16 v[110:113], v[142:145], v[182:185], v[110:113]
	v_mfma_f32_16x16x32_bf16 v[106:109], v[150:153], v[182:185], v[106:109]
	v_mfma_f32_16x16x32_bf16 v[94:97], v[142:145], v[190:193], v[94:97]
	v_mfma_f32_16x16x32_bf16 v[90:93], v[150:153], v[190:193], v[90:93]
	s_waitcnt lgkmcnt(0)
	v_mfma_f32_16x16x32_bf16 v[78:81], v[142:145], v[198:201], v[78:81]
	v_mfma_f32_16x16x32_bf16 v[74:77], v[150:153], v[198:201], v[74:77]
	s_setprio 0
	s_setprio 1
	v_mfma_f32_16x16x32_bf16 v[118:121], v[154:157], v[170:173], v[118:121]
	v_mfma_f32_16x16x32_bf16 v[114:117], v[162:165], v[170:173], v[114:117]
	v_mfma_f32_16x16x32_bf16 v[102:105], v[154:157], v[178:181], v[102:105]
	v_mfma_f32_16x16x32_bf16 v[98:101], v[162:165], v[178:181], v[98:101]
	v_mfma_f32_16x16x32_bf16 v[86:89], v[154:157], v[186:189], v[86:89]
	v_mfma_f32_16x16x32_bf16 v[82:85], v[162:165], v[186:189], v[82:85]
	v_mfma_f32_16x16x32_bf16 v[70:73], v[154:157], v[194:197], v[70:73]
	v_mfma_f32_16x16x32_bf16 v[66:69], v[162:165], v[194:197], v[66:69]
	v_mfma_f32_16x16x32_bf16 v[118:121], v[158:161], v[174:177], v[118:121]
	v_mfma_f32_16x16x32_bf16 v[114:117], v[166:169], v[174:177], v[114:117]
	v_mfma_f32_16x16x32_bf16 v[102:105], v[158:161], v[182:185], v[102:105]
	v_mfma_f32_16x16x32_bf16 v[98:101], v[166:169], v[182:185], v[98:101]
	v_mfma_f32_16x16x32_bf16 v[86:89], v[158:161], v[190:193], v[86:89]
	v_mfma_f32_16x16x32_bf16 v[82:85], v[166:169], v[190:193], v[82:85]
	v_mfma_f32_16x16x32_bf16 v[70:73], v[158:161], v[198:201], v[70:73]
	v_mfma_f32_16x16x32_bf16 v[66:69], v[166:169], v[198:201], v[66:69]
	s_setprio 0
	s_barrier
	ds_read_b128 v[170:173], v133 offset:16384
	ds_read_b128 v[174:177], v133 offset:17408
	s_mov_b32 m0, s33
	s_nop 0
	buffer_load_dwordx4 v130, s[8:11], s62 offen lds
	ds_read_b128 v[178:181], v133 offset:18432
	ds_read_b128 v[182:185], v133 offset:19456
	s_add_i32 s63, s62, 0x40000
	s_mov_b32 m0, s35
	s_nop 0
	buffer_load_dwordx4 v131, s[8:11], s62 offen lds
	ds_read_b128 v[186:189], v133 offset:20480
	ds_read_b128 v[190:193], v133 offset:21504
	s_nop 0
	s_mov_b32 m0, s36
	s_nop 0
	buffer_load_dwordx4 v130, s[8:11], s63 offen lds
	ds_read_b128 v[194:197], v133 offset:22528
	ds_read_b128 v[198:201], v133 offset:23552
	s_nop 0
	s_mov_b32 m0, s37
	s_nop 0
	buffer_load_dwordx4 v131, s[8:11], s63 offen lds
	s_nop 0
	s_mov_b32 m0, s31
	s_nop 0
	buffer_load_dwordx4 v130, s[12:15], s64 offen lds
	s_nop 0
	s_mov_b32 m0, s40
	s_nop 0
	buffer_load_dwordx4 v131, s[12:15], s64 offen lds
	s_waitcnt vmcnt(8)
	s_waitcnt lgkmcnt(0)
	s_barrier
	s_setprio 1
	s_waitcnt lgkmcnt(7)
	v_mfma_f32_16x16x32_bf16 v[62:65], v[134:137], v[170:173], v[62:65]
	v_mfma_f32_16x16x32_bf16 v[58:61], v[146:149], v[170:173], v[58:61]
	s_waitcnt lgkmcnt(5)
	v_mfma_f32_16x16x32_bf16 v[46:49], v[134:137], v[178:181], v[46:49]
	v_mfma_f32_16x16x32_bf16 v[42:45], v[146:149], v[178:181], v[42:45]
	s_waitcnt lgkmcnt(3)
	v_mfma_f32_16x16x32_bf16 v[30:33], v[134:137], v[186:189], v[30:33]
	v_mfma_f32_16x16x32_bf16 v[26:29], v[146:149], v[186:189], v[26:29]
	s_waitcnt lgkmcnt(1)
	v_mfma_f32_16x16x32_bf16 v[14:17], v[134:137], v[194:197], v[14:17]
	v_mfma_f32_16x16x32_bf16 v[10:13], v[146:149], v[194:197], v[10:13]
	v_mfma_f32_16x16x32_bf16 v[62:65], v[142:145], v[174:177], v[62:65]
	v_mfma_f32_16x16x32_bf16 v[58:61], v[150:153], v[174:177], v[58:61]
	v_mfma_f32_16x16x32_bf16 v[46:49], v[142:145], v[182:185], v[46:49]
	v_mfma_f32_16x16x32_bf16 v[42:45], v[150:153], v[182:185], v[42:45]
	v_mfma_f32_16x16x32_bf16 v[30:33], v[142:145], v[190:193], v[30:33]
	v_mfma_f32_16x16x32_bf16 v[26:29], v[150:153], v[190:193], v[26:29]
	s_waitcnt lgkmcnt(0)
	v_mfma_f32_16x16x32_bf16 v[14:17], v[142:145], v[198:201], v[14:17]
	v_mfma_f32_16x16x32_bf16 v[10:13], v[150:153], v[198:201], v[10:13]
	s_setprio 0
	s_setprio 1
	v_mfma_f32_16x16x32_bf16 v[54:57], v[154:157], v[170:173], v[54:57]
	v_mfma_f32_16x16x32_bf16 v[50:53], v[162:165], v[170:173], v[50:53]
	v_mfma_f32_16x16x32_bf16 v[38:41], v[154:157], v[178:181], v[38:41]
	v_mfma_f32_16x16x32_bf16 v[34:37], v[162:165], v[178:181], v[34:37]
	v_mfma_f32_16x16x32_bf16 v[22:25], v[154:157], v[186:189], v[22:25]
	v_mfma_f32_16x16x32_bf16 v[18:21], v[162:165], v[186:189], v[18:21]
	v_mfma_f32_16x16x32_bf16 v[6:9], v[154:157], v[194:197], v[6:9]
	v_mfma_f32_16x16x32_bf16 v[2:5], v[162:165], v[194:197], v[2:5]
	v_mfma_f32_16x16x32_bf16 v[54:57], v[158:161], v[174:177], v[54:57]
	v_mfma_f32_16x16x32_bf16 v[50:53], v[166:169], v[174:177], v[50:53]
	v_mfma_f32_16x16x32_bf16 v[38:41], v[158:161], v[182:185], v[38:41]
	v_mfma_f32_16x16x32_bf16 v[34:37], v[166:169], v[182:185], v[34:37]
	v_mfma_f32_16x16x32_bf16 v[22:25], v[158:161], v[190:193], v[22:25]
	v_mfma_f32_16x16x32_bf16 v[18:21], v[166:169], v[190:193], v[18:21]
	v_mfma_f32_16x16x32_bf16 v[6:9], v[158:161], v[198:201], v[6:9]
	v_mfma_f32_16x16x32_bf16 v[2:5], v[166:169], v[198:201], v[2:5]
	s_setprio 0
	s_barrier
	v_add_u32_e32 v150, 0x18000, v132
	v_add_u32_e32 v166, 0x1c000, v132
	ds_read_b128 v[134:137], v150
	ds_read_b128 v[142:145], v150 offset:1024
	ds_read_b128 v[146:149], v150 offset:2048
	ds_read_b128 v[150:153], v150 offset:3072
	ds_read_b128 v[154:157], v166
	ds_read_b128 v[158:161], v166 offset:1024
	ds_read_b128 v[162:165], v166 offset:2048
	ds_read_b128 v[166:169], v166 offset:3072
	s_add_i32 s63, s64, 0x40000
	s_mov_b32 m0, s41
	s_nop 0
	buffer_load_dwordx4 v130, s[12:15], s63 offen lds
	s_nop 0
	s_mov_b32 m0, s42
	s_nop 0
	buffer_load_dwordx4 v131, s[12:15], s63 offen lds
	ds_read_b128 v[170:173], v133 offset:32768
	ds_read_b128 v[174:177], v133 offset:33792
	ds_read_b128 v[178:181], v133 offset:34816
	ds_read_b128 v[182:185], v133 offset:35840
	ds_read_b128 v[186:189], v133 offset:36864
	ds_read_b128 v[190:193], v133 offset:37888
	ds_read_b128 v[194:197], v133 offset:38912
	ds_read_b128 v[198:201], v133 offset:39936
	s_waitcnt vmcnt(8)
	s_waitcnt lgkmcnt(0)
	s_barrier
	s_setprio 1
	s_waitcnt lgkmcnt(7)
	v_mfma_f32_16x16x32_bf16 v[138:141], v[134:137], v[170:173], v[138:141]
	v_mfma_f32_16x16x32_bf16 v[126:129], v[146:149], v[170:173], v[126:129]
	s_waitcnt lgkmcnt(5)
	v_mfma_f32_16x16x32_bf16 v[110:113], v[134:137], v[178:181], v[110:113]
	v_mfma_f32_16x16x32_bf16 v[106:109], v[146:149], v[178:181], v[106:109]
	s_waitcnt lgkmcnt(3)
	v_mfma_f32_16x16x32_bf16 v[94:97], v[134:137], v[186:189], v[94:97]
	v_mfma_f32_16x16x32_bf16 v[90:93], v[146:149], v[186:189], v[90:93]
	s_waitcnt lgkmcnt(1)
	v_mfma_f32_16x16x32_bf16 v[78:81], v[134:137], v[194:197], v[78:81]
	v_mfma_f32_16x16x32_bf16 v[74:77], v[146:149], v[194:197], v[74:77]
	v_mfma_f32_16x16x32_bf16 v[138:141], v[142:145], v[174:177], v[138:141]
	v_mfma_f32_16x16x32_bf16 v[126:129], v[150:153], v[174:177], v[126:129]
	v_mfma_f32_16x16x32_bf16 v[110:113], v[142:145], v[182:185], v[110:113]
	v_mfma_f32_16x16x32_bf16 v[106:109], v[150:153], v[182:185], v[106:109]
	v_mfma_f32_16x16x32_bf16 v[94:97], v[142:145], v[190:193], v[94:97]
	v_mfma_f32_16x16x32_bf16 v[90:93], v[150:153], v[190:193], v[90:93]
	s_waitcnt lgkmcnt(0)
	v_mfma_f32_16x16x32_bf16 v[78:81], v[142:145], v[198:201], v[78:81]
	v_mfma_f32_16x16x32_bf16 v[74:77], v[150:153], v[198:201], v[74:77]
	s_setprio 0
	s_setprio 1
	v_mfma_f32_16x16x32_bf16 v[118:121], v[154:157], v[170:173], v[118:121]
	v_mfma_f32_16x16x32_bf16 v[114:117], v[162:165], v[170:173], v[114:117]
	v_mfma_f32_16x16x32_bf16 v[102:105], v[154:157], v[178:181], v[102:105]
	v_mfma_f32_16x16x32_bf16 v[98:101], v[162:165], v[178:181], v[98:101]
	v_mfma_f32_16x16x32_bf16 v[86:89], v[154:157], v[186:189], v[86:89]
	v_mfma_f32_16x16x32_bf16 v[82:85], v[162:165], v[186:189], v[82:85]
	v_mfma_f32_16x16x32_bf16 v[70:73], v[154:157], v[194:197], v[70:73]
	v_mfma_f32_16x16x32_bf16 v[66:69], v[162:165], v[194:197], v[66:69]
	v_mfma_f32_16x16x32_bf16 v[118:121], v[158:161], v[174:177], v[118:121]
	v_mfma_f32_16x16x32_bf16 v[114:117], v[166:169], v[174:177], v[114:117]
	v_mfma_f32_16x16x32_bf16 v[102:105], v[158:161], v[182:185], v[102:105]
	v_mfma_f32_16x16x32_bf16 v[98:101], v[166:169], v[182:185], v[98:101]
	v_mfma_f32_16x16x32_bf16 v[86:89], v[158:161], v[190:193], v[86:89]
	v_mfma_f32_16x16x32_bf16 v[82:85], v[166:169], v[190:193], v[82:85]
	v_mfma_f32_16x16x32_bf16 v[70:73], v[158:161], v[198:201], v[70:73]
	v_mfma_f32_16x16x32_bf16 v[66:69], v[166:169], v[198:201], v[66:69]
	s_setprio 0
	s_barrier
	ds_read_b128 v[170:173], v133 offset:49152
	ds_read_b128 v[174:177], v133 offset:50176
	s_or_b32 s63, s62, 0x80
	s_mov_b32 m0, s43
	s_nop 0
	buffer_load_dwordx4 v130, s[8:11], s63 offen lds
	ds_read_b128 v[178:181], v133 offset:51200
	ds_read_b128 v[182:185], v133 offset:52224
	s_add_i32 s62, s62, 0x40080
	s_mov_b32 m0, s44
	s_nop 0
	buffer_load_dwordx4 v131, s[8:11], s63 offen lds
	ds_read_b128 v[186:189], v133 offset:53248
	ds_read_b128 v[190:193], v133 offset:54272
	s_nop 0
	s_mov_b32 m0, s47
	s_nop 0
	buffer_load_dwordx4 v130, s[8:11], s62 offen lds
	ds_read_b128 v[194:197], v133 offset:55296
	ds_read_b128 v[198:201], v133 offset:56320
	s_nop 0
	s_mov_b32 m0, s48
	s_nop 0
	buffer_load_dwordx4 v131, s[8:11], s62 offen lds
	s_nop 0
	s_mov_b32 m0, s45
	s_nop 0
	buffer_load_dwordx4 v130, s[12:15], s61 offen lds
	s_nop 0
	s_mov_b32 m0, s46
	s_nop 0
	buffer_load_dwordx4 v131, s[12:15], s61 offen lds
	s_waitcnt vmcnt(8)
	s_waitcnt lgkmcnt(0)
	s_barrier
	s_setprio 1
	s_waitcnt lgkmcnt(7)
	v_mfma_f32_16x16x32_bf16 v[62:65], v[134:137], v[170:173], v[62:65]
	v_mfma_f32_16x16x32_bf16 v[58:61], v[146:149], v[170:173], v[58:61]
	s_waitcnt lgkmcnt(5)
	v_mfma_f32_16x16x32_bf16 v[46:49], v[134:137], v[178:181], v[46:49]
	v_mfma_f32_16x16x32_bf16 v[42:45], v[146:149], v[178:181], v[42:45]
	s_waitcnt lgkmcnt(3)
	v_mfma_f32_16x16x32_bf16 v[30:33], v[134:137], v[186:189], v[30:33]
	v_mfma_f32_16x16x32_bf16 v[26:29], v[146:149], v[186:189], v[26:29]
	s_waitcnt lgkmcnt(1)
	v_mfma_f32_16x16x32_bf16 v[14:17], v[134:137], v[194:197], v[14:17]
	v_mfma_f32_16x16x32_bf16 v[10:13], v[146:149], v[194:197], v[10:13]
	v_mfma_f32_16x16x32_bf16 v[62:65], v[142:145], v[174:177], v[62:65]
	v_mfma_f32_16x16x32_bf16 v[58:61], v[150:153], v[174:177], v[58:61]
	v_mfma_f32_16x16x32_bf16 v[46:49], v[142:145], v[182:185], v[46:49]
	v_mfma_f32_16x16x32_bf16 v[42:45], v[150:153], v[182:185], v[42:45]
	v_mfma_f32_16x16x32_bf16 v[30:33], v[142:145], v[190:193], v[30:33]
	v_mfma_f32_16x16x32_bf16 v[26:29], v[150:153], v[190:193], v[26:29]
	s_waitcnt lgkmcnt(0)
	v_mfma_f32_16x16x32_bf16 v[14:17], v[142:145], v[198:201], v[14:17]
	v_mfma_f32_16x16x32_bf16 v[10:13], v[150:153], v[198:201], v[10:13]
	s_setprio 0
	s_setprio 1
	v_mfma_f32_16x16x32_bf16 v[54:57], v[154:157], v[170:173], v[54:57]
	v_mfma_f32_16x16x32_bf16 v[50:53], v[162:165], v[170:173], v[50:53]
	v_mfma_f32_16x16x32_bf16 v[38:41], v[154:157], v[178:181], v[38:41]
	v_mfma_f32_16x16x32_bf16 v[34:37], v[162:165], v[178:181], v[34:37]
	v_mfma_f32_16x16x32_bf16 v[22:25], v[154:157], v[186:189], v[22:25]
	v_mfma_f32_16x16x32_bf16 v[18:21], v[162:165], v[186:189], v[18:21]
	v_mfma_f32_16x16x32_bf16 v[6:9], v[154:157], v[194:197], v[6:9]
	v_mfma_f32_16x16x32_bf16 v[2:5], v[162:165], v[194:197], v[2:5]
	v_mfma_f32_16x16x32_bf16 v[54:57], v[158:161], v[174:177], v[54:57]
	v_mfma_f32_16x16x32_bf16 v[50:53], v[166:169], v[174:177], v[50:53]
	v_mfma_f32_16x16x32_bf16 v[38:41], v[158:161], v[182:185], v[38:41]
	v_mfma_f32_16x16x32_bf16 v[34:37], v[166:169], v[182:185], v[34:37]
	v_mfma_f32_16x16x32_bf16 v[22:25], v[158:161], v[190:193], v[22:25]
	v_mfma_f32_16x16x32_bf16 v[18:21], v[166:169], v[190:193], v[18:21]
	v_mfma_f32_16x16x32_bf16 v[6:9], v[158:161], v[198:201], v[6:9]
	v_mfma_f32_16x16x32_bf16 v[2:5], v[166:169], v[198:201], v[2:5]
	s_setprio 0
	s_add_i32 s59, s59, 2
	s_addk_i32 s60, 0x100
	s_cmp_gt_u32 s59, 13
	s_barrier
	s_cbranch_scc0 .LBB0_223
	s_andn2_b64 vcc, exec, s[6:7]
	s_cbranch_vccnz .LBB0_215
	v_mov_b32_e32 v2, 0
	s_mov_b32 s18, s52
	s_mov_b32 s29, s53
	s_mov_b32 s34, s3
	s_mov_b32 s39, s2
	s_mov_b32 s51, s54
	v_mov_b32_e32 v3, v2
	v_mov_b32_e32 v4, v2
	v_mov_b32_e32 v5, v2
	v_mov_b32_e32 v6, v2
	v_mov_b32_e32 v7, v2
	v_mov_b32_e32 v8, v2
	v_mov_b32_e32 v9, v2
	v_mov_b32_e32 v18, v2
	v_mov_b32_e32 v19, v2
	v_mov_b32_e32 v20, v2
	v_mov_b32_e32 v21, v2
	v_mov_b32_e32 v22, v2
	v_mov_b32_e32 v23, v2
	v_mov_b32_e32 v24, v2
	v_mov_b32_e32 v25, v2
	v_mov_b32_e32 v34, v2
	v_mov_b32_e32 v35, v2
	v_mov_b32_e32 v36, v2
	v_mov_b32_e32 v37, v2
	v_mov_b32_e32 v38, v2
	v_mov_b32_e32 v39, v2
	v_mov_b32_e32 v40, v2
	v_mov_b32_e32 v41, v2
	v_mov_b32_e32 v50, v2
	v_mov_b32_e32 v51, v2
	v_mov_b32_e32 v52, v2
	v_mov_b32_e32 v53, v2
	v_mov_b32_e32 v54, v2
	v_mov_b32_e32 v55, v2
	v_mov_b32_e32 v56, v2
	v_mov_b32_e32 v57, v2
	v_mov_b32_e32 v10, v2
	v_mov_b32_e32 v11, v2
	v_mov_b32_e32 v12, v2
	v_mov_b32_e32 v13, v2
	v_mov_b32_e32 v14, v2
	v_mov_b32_e32 v15, v2
	v_mov_b32_e32 v16, v2
	v_mov_b32_e32 v17, v2
	v_mov_b32_e32 v26, v2
	v_mov_b32_e32 v27, v2
	v_mov_b32_e32 v28, v2
	v_mov_b32_e32 v29, v2
	v_mov_b32_e32 v30, v2
	v_mov_b32_e32 v31, v2
	v_mov_b32_e32 v32, v2
	v_mov_b32_e32 v33, v2
	v_mov_b32_e32 v42, v2
	v_mov_b32_e32 v43, v2
	v_mov_b32_e32 v44, v2
	v_mov_b32_e32 v45, v2
	v_mov_b32_e32 v46, v2
	v_mov_b32_e32 v47, v2
	v_mov_b32_e32 v48, v2
	v_mov_b32_e32 v49, v2
	v_mov_b32_e32 v58, v2
	v_mov_b32_e32 v59, v2
	v_mov_b32_e32 v60, v2
	v_mov_b32_e32 v61, v2
	v_mov_b32_e32 v62, v2
	v_mov_b32_e32 v63, v2
	v_mov_b32_e32 v64, v2
	v_mov_b32_e32 v65, v2
	v_mov_b32_e32 v66, v2
	v_mov_b32_e32 v67, v2
	v_mov_b32_e32 v68, v2
	v_mov_b32_e32 v69, v2
	v_mov_b32_e32 v70, v2
	v_mov_b32_e32 v71, v2
	v_mov_b32_e32 v72, v2
	v_mov_b32_e32 v73, v2
	v_mov_b32_e32 v82, v2
	v_mov_b32_e32 v83, v2
	v_mov_b32_e32 v84, v2
	v_mov_b32_e32 v85, v2
	v_mov_b32_e32 v86, v2
	v_mov_b32_e32 v87, v2
	v_mov_b32_e32 v88, v2
	v_mov_b32_e32 v89, v2
	v_mov_b32_e32 v98, v2
	v_mov_b32_e32 v99, v2
	v_mov_b32_e32 v100, v2
	v_mov_b32_e32 v101, v2
	v_mov_b32_e32 v102, v2
	v_mov_b32_e32 v103, v2
	v_mov_b32_e32 v104, v2
	v_mov_b32_e32 v105, v2
	v_mov_b32_e32 v114, v2
	v_mov_b32_e32 v115, v2
	v_mov_b32_e32 v116, v2
	v_mov_b32_e32 v117, v2
	v_mov_b32_e32 v118, v2
	v_mov_b32_e32 v119, v2
	v_mov_b32_e32 v120, v2
	v_mov_b32_e32 v121, v2
	v_mov_b32_e32 v74, v2
	v_mov_b32_e32 v75, v2
	v_mov_b32_e32 v76, v2
	v_mov_b32_e32 v77, v2
	v_mov_b32_e32 v78, v2
	v_mov_b32_e32 v79, v2
	v_mov_b32_e32 v80, v2
	v_mov_b32_e32 v81, v2
	v_mov_b32_e32 v90, v2
	v_mov_b32_e32 v91, v2
	v_mov_b32_e32 v92, v2
	v_mov_b32_e32 v93, v2
	v_mov_b32_e32 v94, v2
	v_mov_b32_e32 v95, v2
	v_mov_b32_e32 v96, v2
	v_mov_b32_e32 v97, v2
	v_mov_b32_e32 v106, v2
	v_mov_b32_e32 v107, v2
	v_mov_b32_e32 v108, v2
	v_mov_b32_e32 v109, v2
	v_mov_b32_e32 v110, v2
	v_mov_b32_e32 v111, v2
	v_mov_b32_e32 v112, v2
	v_mov_b32_e32 v113, v2
	v_mov_b32_e32 v126, v2
	v_mov_b32_e32 v127, v2
	v_mov_b32_e32 v128, v2
	v_mov_b32_e32 v129, v2
	v_mov_b32_e32 v138, v2
	v_mov_b32_e32 v139, v2
	v_mov_b32_e32 v140, v2
	v_mov_b32_e32 v141, v2
	s_branch .LBB0_215

.LBB0_353:
	ds_read_b128 v[136:139], v153
	ds_read_b128 v[140:143], v153 offset:1024
	ds_read_b128 v[158:161], v153 offset:2048
	ds_read_b128 v[162:165], v153 offset:3072
	ds_read_b128 v[166:169], v154
	ds_read_b128 v[170:173], v154 offset:1024
	ds_read_b128 v[174:177], v154 offset:2048
	ds_read_b128 v[178:181], v154 offset:3072
	s_add_i32 s66, s63, 0xfffe0080
	s_cmp_eq_u32 s65, 4
	s_cselect_b32 s68, s1, s66
	s_cselect_b32 s67, s62, s64
	s_or_b32 s66, s68, 0x80
	s_mov_b32 m0, s48
	s_nop 0
	buffer_load_dwordx4 v147, s[12:15], s63 offen lds
	s_nop 0
	s_mov_b32 m0, s49
	s_nop 0
	buffer_load_dwordx4 v148, s[12:15], s63 offen lds
	ds_read_b128 v[182:185], v155
	ds_read_b128 v[186:189], v155 offset:1024
	ds_read_b128 v[190:193], v155 offset:2048
	ds_read_b128 v[194:197], v155 offset:3072
	ds_read_b128 v[198:201], v155 offset:4096
	ds_read_b128 v[202:205], v155 offset:5120
	ds_read_b128 v[206:209], v155 offset:6144
	ds_read_b128 v[210:213], v155 offset:7168
	s_waitcnt vmcnt(8)
	s_waitcnt lgkmcnt(0)
	s_barrier
	s_setprio 1
	s_waitcnt lgkmcnt(0)
	v_mfma_i32_16x16x64_i8 v[126:129], v[136:139], v[182:185], v[126:129]
	v_mfma_i32_16x16x64_i8 v[122:125], v[158:161], v[182:185], v[122:125]
	v_mfma_i32_16x16x64_i8 v[118:121], v[136:139], v[190:193], v[118:121]
	v_mfma_i32_16x16x64_i8 v[114:117], v[158:161], v[190:193], v[114:117]
	v_mfma_i32_16x16x64_i8 v[110:113], v[136:139], v[198:201], v[110:113]
	v_mfma_i32_16x16x64_i8 v[106:109], v[158:161], v[198:201], v[106:109]
	v_mfma_i32_16x16x64_i8 v[102:105], v[136:139], v[206:209], v[102:105]
	v_mfma_i32_16x16x64_i8 v[98:101], v[158:161], v[206:209], v[98:101]
	v_mfma_i32_16x16x64_i8 v[126:129], v[140:143], v[186:189], v[126:129]
	v_mfma_i32_16x16x64_i8 v[122:125], v[162:165], v[186:189], v[122:125]
	v_mfma_i32_16x16x64_i8 v[118:121], v[140:143], v[194:197], v[118:121]
	v_mfma_i32_16x16x64_i8 v[114:117], v[162:165], v[194:197], v[114:117]
	v_mfma_i32_16x16x64_i8 v[110:113], v[140:143], v[202:205], v[110:113]
	v_mfma_i32_16x16x64_i8 v[106:109], v[162:165], v[202:205], v[106:109]
	v_mfma_i32_16x16x64_i8 v[102:105], v[140:143], v[210:213], v[102:105]
	v_mfma_i32_16x16x64_i8 v[98:101], v[162:165], v[210:213], v[98:101]
	s_setprio 0
	s_setprio 1
	v_mfma_i32_16x16x64_i8 v[94:97], v[166:169], v[182:185], v[94:97]
	v_mfma_i32_16x16x64_i8 v[90:93], v[174:177], v[182:185], v[90:93]
	v_mfma_i32_16x16x64_i8 v[86:89], v[166:169], v[190:193], v[86:89]
	v_mfma_i32_16x16x64_i8 v[82:85], v[174:177], v[190:193], v[82:85]
	v_mfma_i32_16x16x64_i8 v[78:81], v[166:169], v[198:201], v[78:81]
	v_mfma_i32_16x16x64_i8 v[74:77], v[174:177], v[198:201], v[74:77]
	v_mfma_i32_16x16x64_i8 v[70:73], v[166:169], v[206:209], v[70:73]
	v_mfma_i32_16x16x64_i8 v[66:69], v[174:177], v[206:209], v[66:69]
	v_mfma_i32_16x16x64_i8 v[94:97], v[170:173], v[186:189], v[94:97]
	v_mfma_i32_16x16x64_i8 v[90:93], v[178:181], v[186:189], v[90:93]
	v_mfma_i32_16x16x64_i8 v[86:89], v[170:173], v[194:197], v[86:89]
	v_mfma_i32_16x16x64_i8 v[82:85], v[178:181], v[194:197], v[82:85]
	v_mfma_i32_16x16x64_i8 v[78:81], v[170:173], v[202:205], v[78:81]
	v_mfma_i32_16x16x64_i8 v[74:77], v[178:181], v[202:205], v[74:77]
	v_mfma_i32_16x16x64_i8 v[70:73], v[170:173], v[210:213], v[70:73]
	v_mfma_i32_16x16x64_i8 v[66:69], v[178:181], v[210:213], v[66:69]
	s_setprio 0
	s_barrier
	ds_read_b128 v[182:185], v155 offset:16384
	ds_read_b128 v[186:189], v155 offset:17408
	s_mov_b32 m0, s34
	s_nop 0
	buffer_load_dwordx4 v145, s[8:11], s67 offen lds
	ds_read_b128 v[190:193], v155 offset:18432
	ds_read_b128 v[194:197], v155 offset:19456
	s_add_i32 s69, s67, 0x20000
	s_mov_b32 m0, s35
	s_nop 0
	buffer_load_dwordx4 v146, s[8:11], s67 offen lds
	ds_read_b128 v[198:201], v155 offset:20480
	ds_read_b128 v[202:205], v155 offset:21504
	s_nop 0
	s_mov_b32 m0, s36
	s_nop 0
	buffer_load_dwordx4 v145, s[8:11], s69 offen lds
	ds_read_b128 v[206:209], v155 offset:22528
	ds_read_b128 v[210:213], v155 offset:23552
	s_nop 0
	s_mov_b32 m0, s37
	s_nop 0
	buffer_load_dwordx4 v146, s[8:11], s69 offen lds
	s_nop 0
	s_mov_b32 m0, s33
	s_nop 0
	buffer_load_dwordx4 v147, s[12:15], s68 offen lds
	s_nop 0
	s_mov_b32 m0, s2
	s_nop 0
	buffer_load_dwordx4 v148, s[12:15], s68 offen lds
	s_waitcnt vmcnt(8)
	s_waitcnt lgkmcnt(0)
	s_barrier
	s_setprio 1
	s_waitcnt lgkmcnt(0)
	v_mfma_i32_16x16x64_i8 v[62:65], v[136:139], v[182:185], v[62:65]
	v_mfma_i32_16x16x64_i8 v[58:61], v[158:161], v[182:185], v[58:61]
	v_mfma_i32_16x16x64_i8 v[54:57], v[136:139], v[190:193], v[54:57]
	v_mfma_i32_16x16x64_i8 v[50:53], v[158:161], v[190:193], v[50:53]
	v_mfma_i32_16x16x64_i8 v[46:49], v[136:139], v[198:201], v[46:49]
	v_mfma_i32_16x16x64_i8 v[42:45], v[158:161], v[198:201], v[42:45]
	v_mfma_i32_16x16x64_i8 v[38:41], v[136:139], v[206:209], v[38:41]
	v_mfma_i32_16x16x64_i8 v[34:37], v[158:161], v[206:209], v[34:37]
	v_mfma_i32_16x16x64_i8 v[62:65], v[140:143], v[186:189], v[62:65]
	v_mfma_i32_16x16x64_i8 v[58:61], v[162:165], v[186:189], v[58:61]
	v_mfma_i32_16x16x64_i8 v[54:57], v[140:143], v[194:197], v[54:57]
	v_mfma_i32_16x16x64_i8 v[50:53], v[162:165], v[194:197], v[50:53]
	v_mfma_i32_16x16x64_i8 v[46:49], v[140:143], v[202:205], v[46:49]
	v_mfma_i32_16x16x64_i8 v[42:45], v[162:165], v[202:205], v[42:45]
	v_mfma_i32_16x16x64_i8 v[38:41], v[140:143], v[210:213], v[38:41]
	v_mfma_i32_16x16x64_i8 v[34:37], v[162:165], v[210:213], v[34:37]
	s_setprio 0
	s_setprio 1
	v_mfma_i32_16x16x64_i8 v[30:33], v[166:169], v[182:185], v[30:33]
	v_mfma_i32_16x16x64_i8 v[26:29], v[174:177], v[182:185], v[26:29]
	v_mfma_i32_16x16x64_i8 v[22:25], v[166:169], v[190:193], v[22:25]
	v_mfma_i32_16x16x64_i8 v[18:21], v[174:177], v[190:193], v[18:21]
	v_mfma_i32_16x16x64_i8 v[14:17], v[166:169], v[198:201], v[14:17]
	v_mfma_i32_16x16x64_i8 v[10:13], v[174:177], v[198:201], v[10:13]
	v_mfma_i32_16x16x64_i8 v[6:9], v[166:169], v[206:209], v[6:9]
	v_mfma_i32_16x16x64_i8 v[2:5], v[174:177], v[206:209], v[2:5]
	v_mfma_i32_16x16x64_i8 v[30:33], v[170:173], v[186:189], v[30:33]
	v_mfma_i32_16x16x64_i8 v[26:29], v[178:181], v[186:189], v[26:29]
	v_mfma_i32_16x16x64_i8 v[22:25], v[170:173], v[194:197], v[22:25]
	v_mfma_i32_16x16x64_i8 v[18:21], v[178:181], v[194:197], v[18:21]
	v_mfma_i32_16x16x64_i8 v[14:17], v[170:173], v[202:205], v[14:17]
	v_mfma_i32_16x16x64_i8 v[10:13], v[178:181], v[202:205], v[10:13]
	v_mfma_i32_16x16x64_i8 v[6:9], v[170:173], v[210:213], v[6:9]
	v_mfma_i32_16x16x64_i8 v[2:5], v[178:181], v[210:213], v[2:5]
	s_setprio 0
	s_barrier
	ds_read_b128 v[136:139], v156
	ds_read_b128 v[140:143], v156 offset:1024
	ds_read_b128 v[158:161], v156 offset:2048
	ds_read_b128 v[162:165], v156 offset:3072
	ds_read_b128 v[166:169], v157
	ds_read_b128 v[170:173], v157 offset:1024
	ds_read_b128 v[174:177], v157 offset:2048
	ds_read_b128 v[178:181], v157 offset:3072
	s_add_i32 s68, s68, 0x20000
	s_mov_b32 m0, s3
	s_nop 0
	buffer_load_dwordx4 v147, s[12:15], s68 offen lds
	s_nop 0
	s_mov_b32 m0, s38
	s_nop 0
	buffer_load_dwordx4 v148, s[12:15], s68 offen lds
	ds_read_b128 v[182:185], v155 offset:32768
	ds_read_b128 v[186:189], v155 offset:33792
	ds_read_b128 v[190:193], v155 offset:34816
	ds_read_b128 v[194:197], v155 offset:35840
	ds_read_b128 v[198:201], v155 offset:36864
	ds_read_b128 v[202:205], v155 offset:37888
	ds_read_b128 v[206:209], v155 offset:38912
	ds_read_b128 v[210:213], v155 offset:39936
	s_waitcnt vmcnt(8)
	s_waitcnt lgkmcnt(0)
	s_barrier
	s_setprio 1
	s_waitcnt lgkmcnt(0)
	v_mfma_i32_16x16x64_i8 v[126:129], v[136:139], v[182:185], v[126:129]
	v_mfma_i32_16x16x64_i8 v[122:125], v[158:161], v[182:185], v[122:125]
	v_mfma_i32_16x16x64_i8 v[118:121], v[136:139], v[190:193], v[118:121]
	v_mfma_i32_16x16x64_i8 v[114:117], v[158:161], v[190:193], v[114:117]
	v_mfma_i32_16x16x64_i8 v[110:113], v[136:139], v[198:201], v[110:113]
	v_mfma_i32_16x16x64_i8 v[106:109], v[158:161], v[198:201], v[106:109]
	v_mfma_i32_16x16x64_i8 v[102:105], v[136:139], v[206:209], v[102:105]
	v_mfma_i32_16x16x64_i8 v[98:101], v[158:161], v[206:209], v[98:101]
	v_mfma_i32_16x16x64_i8 v[126:129], v[140:143], v[186:189], v[126:129]
	v_mfma_i32_16x16x64_i8 v[122:125], v[162:165], v[186:189], v[122:125]
	v_mfma_i32_16x16x64_i8 v[118:121], v[140:143], v[194:197], v[118:121]
	v_mfma_i32_16x16x64_i8 v[114:117], v[162:165], v[194:197], v[114:117]
	v_mfma_i32_16x16x64_i8 v[110:113], v[140:143], v[202:205], v[110:113]
	v_mfma_i32_16x16x64_i8 v[106:109], v[162:165], v[202:205], v[106:109]
	v_mfma_i32_16x16x64_i8 v[102:105], v[140:143], v[210:213], v[102:105]
	v_mfma_i32_16x16x64_i8 v[98:101], v[162:165], v[210:213], v[98:101]
	s_setprio 0
	s_setprio 1
	v_mfma_i32_16x16x64_i8 v[94:97], v[166:169], v[182:185], v[94:97]
	v_mfma_i32_16x16x64_i8 v[90:93], v[174:177], v[182:185], v[90:93]
	v_mfma_i32_16x16x64_i8 v[86:89], v[166:169], v[190:193], v[86:89]
	v_mfma_i32_16x16x64_i8 v[82:85], v[174:177], v[190:193], v[82:85]
	v_mfma_i32_16x16x64_i8 v[78:81], v[166:169], v[198:201], v[78:81]
	v_mfma_i32_16x16x64_i8 v[74:77], v[174:177], v[198:201], v[74:77]
	v_mfma_i32_16x16x64_i8 v[70:73], v[166:169], v[206:209], v[70:73]
	v_mfma_i32_16x16x64_i8 v[66:69], v[174:177], v[206:209], v[66:69]
	v_mfma_i32_16x16x64_i8 v[94:97], v[170:173], v[186:189], v[94:97]
	v_mfma_i32_16x16x64_i8 v[90:93], v[178:181], v[186:189], v[90:93]
	v_mfma_i32_16x16x64_i8 v[86:89], v[170:173], v[194:197], v[86:89]
	v_mfma_i32_16x16x64_i8 v[82:85], v[178:181], v[194:197], v[82:85]
	v_mfma_i32_16x16x64_i8 v[78:81], v[170:173], v[202:205], v[78:81]
	v_mfma_i32_16x16x64_i8 v[74:77], v[178:181], v[202:205], v[74:77]
	v_mfma_i32_16x16x64_i8 v[70:73], v[170:173], v[210:213], v[70:73]
	v_mfma_i32_16x16x64_i8 v[66:69], v[178:181], v[210:213], v[66:69]
	s_setprio 0
	s_barrier
	ds_read_b128 v[182:185], v155 offset:49152
	ds_read_b128 v[186:189], v155 offset:50176
	s_or_b32 s68, s67, 0x80
	s_mov_b32 m0, s41
	s_nop 0
	buffer_load_dwordx4 v145, s[8:11], s68 offen lds
	ds_read_b128 v[190:193], v155 offset:51200
	ds_read_b128 v[194:197], v155 offset:52224
	s_add_i32 s67, s67, 0x20080
	s_mov_b32 m0, s42
	s_nop 0
	buffer_load_dwordx4 v146, s[8:11], s68 offen lds
	ds_read_b128 v[198:201], v155 offset:53248
	ds_read_b128 v[202:205], v155 offset:54272
	s_nop 0
	s_mov_b32 m0, s45
	s_nop 0
	buffer_load_dwordx4 v145, s[8:11], s67 offen lds
	ds_read_b128 v[206:209], v155 offset:55296
	ds_read_b128 v[210:213], v155 offset:56320
	s_nop 0
	s_mov_b32 m0, s46
	s_nop 0
	buffer_load_dwordx4 v146, s[8:11], s67 offen lds
	s_nop 0
	s_mov_b32 m0, s43
	s_nop 0
	buffer_load_dwordx4 v147, s[12:15], s66 offen lds
	s_nop 0
	s_mov_b32 m0, s44
	s_nop 0
	buffer_load_dwordx4 v148, s[12:15], s66 offen lds
	s_waitcnt vmcnt(8)
	s_waitcnt lgkmcnt(0)
	s_barrier
	s_setprio 1
	s_waitcnt lgkmcnt(0)
	v_mfma_i32_16x16x64_i8 v[62:65], v[136:139], v[182:185], v[62:65]
	v_mfma_i32_16x16x64_i8 v[58:61], v[158:161], v[182:185], v[58:61]
	v_mfma_i32_16x16x64_i8 v[54:57], v[136:139], v[190:193], v[54:57]
	v_mfma_i32_16x16x64_i8 v[50:53], v[158:161], v[190:193], v[50:53]
	v_mfma_i32_16x16x64_i8 v[46:49], v[136:139], v[198:201], v[46:49]
	v_mfma_i32_16x16x64_i8 v[42:45], v[158:161], v[198:201], v[42:45]
	v_mfma_i32_16x16x64_i8 v[38:41], v[136:139], v[206:209], v[38:41]
	v_mfma_i32_16x16x64_i8 v[34:37], v[158:161], v[206:209], v[34:37]
	v_mfma_i32_16x16x64_i8 v[62:65], v[140:143], v[186:189], v[62:65]
	v_mfma_i32_16x16x64_i8 v[58:61], v[162:165], v[186:189], v[58:61]
	v_mfma_i32_16x16x64_i8 v[54:57], v[140:143], v[194:197], v[54:57]
	v_mfma_i32_16x16x64_i8 v[50:53], v[162:165], v[194:197], v[50:53]
	v_mfma_i32_16x16x64_i8 v[46:49], v[140:143], v[202:205], v[46:49]
	v_mfma_i32_16x16x64_i8 v[42:45], v[162:165], v[202:205], v[42:45]
	v_mfma_i32_16x16x64_i8 v[38:41], v[140:143], v[210:213], v[38:41]
	v_mfma_i32_16x16x64_i8 v[34:37], v[162:165], v[210:213], v[34:37]
	s_setprio 0
	s_setprio 1
	v_mfma_i32_16x16x64_i8 v[30:33], v[166:169], v[182:185], v[30:33]
	v_mfma_i32_16x16x64_i8 v[26:29], v[174:177], v[182:185], v[26:29]
	v_mfma_i32_16x16x64_i8 v[22:25], v[166:169], v[190:193], v[22:25]
	v_mfma_i32_16x16x64_i8 v[18:21], v[174:177], v[190:193], v[18:21]
	v_mfma_i32_16x16x64_i8 v[14:17], v[166:169], v[198:201], v[14:17]
	v_mfma_i32_16x16x64_i8 v[10:13], v[174:177], v[198:201], v[10:13]
	v_mfma_i32_16x16x64_i8 v[6:9], v[166:169], v[206:209], v[6:9]
	v_mfma_i32_16x16x64_i8 v[2:5], v[174:177], v[206:209], v[2:5]
	v_mfma_i32_16x16x64_i8 v[30:33], v[170:173], v[186:189], v[30:33]
	v_mfma_i32_16x16x64_i8 v[26:29], v[178:181], v[186:189], v[26:29]
	v_mfma_i32_16x16x64_i8 v[22:25], v[170:173], v[194:197], v[22:25]
	v_mfma_i32_16x16x64_i8 v[18:21], v[178:181], v[194:197], v[18:21]
	v_mfma_i32_16x16x64_i8 v[14:17], v[170:173], v[202:205], v[14:17]
	v_mfma_i32_16x16x64_i8 v[10:13], v[178:181], v[202:205], v[10:13]
	v_mfma_i32_16x16x64_i8 v[6:9], v[170:173], v[210:213], v[6:9]
	v_mfma_i32_16x16x64_i8 v[2:5], v[178:181], v[210:213], v[2:5]
	s_setprio 0
	s_add_i32 s65, s65, 2
	s_addk_i32 s63, 0x100
	s_addk_i32 s64, 0x100
	s_cmp_gt_u32 s65, 5
	s_barrier
	s_cbranch_scc0 .LBB0_353
	s_and_b64 vcc, exec, s[24:25]
	s_cbranch_vccz .LBB0_356
	s_barrier

.LBB0_467:
	v_add_u32_e32 v147, 0x10000, v132
	ds_read_b128 v[138:141], v147
	ds_read_b128 v[142:145], v147 offset:1024
	ds_read_b128 v[148:151], v147 offset:2048
	ds_read_b128 v[152:155], v147 offset:3072
	v_add_u32_e32 v147, 0x14000, v132
	ds_read_b128 v[156:159], v147
	ds_read_b128 v[160:163], v147 offset:1024
	ds_read_b128 v[164:167], v147 offset:2048
	ds_read_b128 v[168:171], v147 offset:3072
	s_add_i32 s59, s3, s1
	s_add_i32 s58, s33, s1
	s_add_i32 s55, s59, 0x1600
	s_addk_i32 s58, 0x1600
	s_cmp_eq_u32 s1, 0
	s_cselect_b32 s60, s53, s55
	s_cselect_b32 s58, s54, s58
	s_add_i32 s55, s60, 0x80
	s_add_i32 s59, s59, 0xb1580
	s_mov_b32 m0, s46
	s_nop 0
	buffer_load_dwordx4 v130, s[12:15], s59 offen lds
	s_nop 0
	s_mov_b32 m0, s47
	s_nop 0
	buffer_load_dwordx4 v131, s[12:15], s59 offen lds
	ds_read_b128 v[172:175], v133
	ds_read_b128 v[176:179], v133 offset:1024
	ds_read_b128 v[180:183], v133 offset:2048
	ds_read_b128 v[184:187], v133 offset:3072
	ds_read_b128 v[188:191], v133 offset:4096
	ds_read_b128 v[192:195], v133 offset:5120
	ds_read_b128 v[196:199], v133 offset:6144
	ds_read_b128 v[200:203], v133 offset:7168
	s_waitcnt vmcnt(8)
	s_waitcnt lgkmcnt(0)
	s_barrier
	s_setprio 1
	s_waitcnt lgkmcnt(7)
	v_mfma_f32_16x16x32_bf16 v[134:137], v[138:141], v[172:175], v[134:137]
	v_mfma_f32_16x16x32_bf16 v[122:125], v[148:151], v[172:175], v[122:125]
	s_waitcnt lgkmcnt(5)
	v_mfma_f32_16x16x32_bf16 v[110:113], v[138:141], v[180:183], v[110:113]
	v_mfma_f32_16x16x32_bf16 v[106:109], v[148:151], v[180:183], v[106:109]
	s_waitcnt lgkmcnt(3)
	v_mfma_f32_16x16x32_bf16 v[94:97], v[138:141], v[188:191], v[94:97]
	v_mfma_f32_16x16x32_bf16 v[90:93], v[148:151], v[188:191], v[90:93]
	s_waitcnt lgkmcnt(1)
	v_mfma_f32_16x16x32_bf16 v[78:81], v[138:141], v[196:199], v[78:81]
	v_mfma_f32_16x16x32_bf16 v[74:77], v[148:151], v[196:199], v[74:77]
	v_mfma_f32_16x16x32_bf16 v[134:137], v[142:145], v[176:179], v[134:137]
	v_mfma_f32_16x16x32_bf16 v[122:125], v[152:155], v[176:179], v[122:125]
	v_mfma_f32_16x16x32_bf16 v[110:113], v[142:145], v[184:187], v[110:113]
	v_mfma_f32_16x16x32_bf16 v[106:109], v[152:155], v[184:187], v[106:109]
	v_mfma_f32_16x16x32_bf16 v[94:97], v[142:145], v[192:195], v[94:97]
	v_mfma_f32_16x16x32_bf16 v[90:93], v[152:155], v[192:195], v[90:93]
	s_waitcnt lgkmcnt(0)
	v_mfma_f32_16x16x32_bf16 v[78:81], v[142:145], v[200:203], v[78:81]
	v_mfma_f32_16x16x32_bf16 v[74:77], v[152:155], v[200:203], v[74:77]
	s_setprio 0
	s_setprio 1
	v_mfma_f32_16x16x32_bf16 v[118:121], v[156:159], v[172:175], v[118:121]
	v_mfma_f32_16x16x32_bf16 v[114:117], v[164:167], v[172:175], v[114:117]
	v_mfma_f32_16x16x32_bf16 v[102:105], v[156:159], v[180:183], v[102:105]
	v_mfma_f32_16x16x32_bf16 v[98:101], v[164:167], v[180:183], v[98:101]
	v_mfma_f32_16x16x32_bf16 v[86:89], v[156:159], v[188:191], v[86:89]
	v_mfma_f32_16x16x32_bf16 v[82:85], v[164:167], v[188:191], v[82:85]
	v_mfma_f32_16x16x32_bf16 v[70:73], v[156:159], v[196:199], v[70:73]
	v_mfma_f32_16x16x32_bf16 v[66:69], v[164:167], v[196:199], v[66:69]
	v_mfma_f32_16x16x32_bf16 v[118:121], v[160:163], v[176:179], v[118:121]
	v_mfma_f32_16x16x32_bf16 v[114:117], v[168:171], v[176:179], v[114:117]
	v_mfma_f32_16x16x32_bf16 v[102:105], v[160:163], v[184:187], v[102:105]
	v_mfma_f32_16x16x32_bf16 v[98:101], v[168:171], v[184:187], v[98:101]
	v_mfma_f32_16x16x32_bf16 v[86:89], v[160:163], v[192:195], v[86:89]
	v_mfma_f32_16x16x32_bf16 v[82:85], v[168:171], v[192:195], v[82:85]
	v_mfma_f32_16x16x32_bf16 v[70:73], v[160:163], v[200:203], v[70:73]
	v_mfma_f32_16x16x32_bf16 v[66:69], v[168:171], v[200:203], v[66:69]
	s_setprio 0
	s_barrier
	ds_read_b128 v[172:175], v133 offset:16384
	ds_read_b128 v[176:179], v133 offset:17408
	s_mov_b32 m0, s29
	s_nop 0
	buffer_load_dwordx4 v130, s[8:11], s58 offen lds
	ds_read_b128 v[180:183], v133 offset:18432
	ds_read_b128 v[184:187], v133 offset:19456
	s_add_i32 s59, s58, 0xb0000
	s_mov_b32 m0, s34
	s_nop 0
	buffer_load_dwordx4 v131, s[8:11], s58 offen lds
	ds_read_b128 v[188:191], v133 offset:20480
	ds_read_b128 v[192:195], v133 offset:21504
	s_nop 0
	s_mov_b32 m0, s35
	s_nop 0
	buffer_load_dwordx4 v130, s[8:11], s59 offen lds
	ds_read_b128 v[196:199], v133 offset:22528
	ds_read_b128 v[200:203], v133 offset:23552
	s_nop 0
	s_mov_b32 m0, s36
	s_nop 0
	buffer_load_dwordx4 v131, s[8:11], s59 offen lds
	s_nop 0
	s_mov_b32 m0, s28
	s_nop 0
	buffer_load_dwordx4 v130, s[12:15], s60 offen lds
	s_nop 0
	s_mov_b32 m0, s37
	s_nop 0
	buffer_load_dwordx4 v131, s[12:15], s60 offen lds
	s_waitcnt vmcnt(8)
	s_waitcnt lgkmcnt(0)
	s_barrier
	s_setprio 1
	s_waitcnt lgkmcnt(7)
	v_mfma_f32_16x16x32_bf16 v[62:65], v[138:141], v[172:175], v[62:65]
	v_mfma_f32_16x16x32_bf16 v[58:61], v[148:151], v[172:175], v[58:61]
	s_waitcnt lgkmcnt(5)
	v_mfma_f32_16x16x32_bf16 v[46:49], v[138:141], v[180:183], v[46:49]
	v_mfma_f32_16x16x32_bf16 v[42:45], v[148:151], v[180:183], v[42:45]
	s_waitcnt lgkmcnt(3)
	v_mfma_f32_16x16x32_bf16 v[30:33], v[138:141], v[188:191], v[30:33]
	v_mfma_f32_16x16x32_bf16 v[26:29], v[148:151], v[188:191], v[26:29]
	s_waitcnt lgkmcnt(1)
	v_mfma_f32_16x16x32_bf16 v[14:17], v[138:141], v[196:199], v[14:17]
	v_mfma_f32_16x16x32_bf16 v[10:13], v[148:151], v[196:199], v[10:13]
	v_mfma_f32_16x16x32_bf16 v[62:65], v[142:145], v[176:179], v[62:65]
	v_mfma_f32_16x16x32_bf16 v[58:61], v[152:155], v[176:179], v[58:61]
	v_mfma_f32_16x16x32_bf16 v[46:49], v[142:145], v[184:187], v[46:49]
	v_mfma_f32_16x16x32_bf16 v[42:45], v[152:155], v[184:187], v[42:45]
	v_mfma_f32_16x16x32_bf16 v[30:33], v[142:145], v[192:195], v[30:33]
	v_mfma_f32_16x16x32_bf16 v[26:29], v[152:155], v[192:195], v[26:29]
	s_waitcnt lgkmcnt(0)
	v_mfma_f32_16x16x32_bf16 v[14:17], v[142:145], v[200:203], v[14:17]
	v_mfma_f32_16x16x32_bf16 v[10:13], v[152:155], v[200:203], v[10:13]
	s_setprio 0
	s_setprio 1
	v_mfma_f32_16x16x32_bf16 v[54:57], v[156:159], v[172:175], v[54:57]
	v_mfma_f32_16x16x32_bf16 v[50:53], v[164:167], v[172:175], v[50:53]
	v_mfma_f32_16x16x32_bf16 v[38:41], v[156:159], v[180:183], v[38:41]
	v_mfma_f32_16x16x32_bf16 v[34:37], v[164:167], v[180:183], v[34:37]
	v_mfma_f32_16x16x32_bf16 v[22:25], v[156:159], v[188:191], v[22:25]
	v_mfma_f32_16x16x32_bf16 v[18:21], v[164:167], v[188:191], v[18:21]
	v_mfma_f32_16x16x32_bf16 v[6:9], v[156:159], v[196:199], v[6:9]
	v_mfma_f32_16x16x32_bf16 v[2:5], v[164:167], v[196:199], v[2:5]
	v_mfma_f32_16x16x32_bf16 v[54:57], v[160:163], v[176:179], v[54:57]
	v_mfma_f32_16x16x32_bf16 v[50:53], v[168:171], v[176:179], v[50:53]
	v_mfma_f32_16x16x32_bf16 v[38:41], v[160:163], v[184:187], v[38:41]
	v_mfma_f32_16x16x32_bf16 v[34:37], v[168:171], v[184:187], v[34:37]
	v_mfma_f32_16x16x32_bf16 v[22:25], v[160:163], v[192:195], v[22:25]
	v_mfma_f32_16x16x32_bf16 v[18:21], v[168:171], v[192:195], v[18:21]
	v_mfma_f32_16x16x32_bf16 v[6:9], v[160:163], v[200:203], v[6:9]
	v_mfma_f32_16x16x32_bf16 v[2:5], v[168:171], v[200:203], v[2:5]
	s_setprio 0
	s_barrier
	v_add_u32_e32 v147, 0x18000, v132
	ds_read_b128 v[138:141], v147
	ds_read_b128 v[142:145], v147 offset:1024
	ds_read_b128 v[148:151], v147 offset:2048
	ds_read_b128 v[152:155], v147 offset:3072
	v_add_u32_e32 v147, 0x1c000, v132
	ds_read_b128 v[156:159], v147
	ds_read_b128 v[160:163], v147 offset:1024
	ds_read_b128 v[164:167], v147 offset:2048
	ds_read_b128 v[168:171], v147 offset:3072
	s_add_i32 s59, s60, 0xb0000
	s_mov_b32 m0, s38
	s_nop 0
	buffer_load_dwordx4 v130, s[12:15], s59 offen lds
	s_nop 0
	s_mov_b32 m0, s39
	s_nop 0
	buffer_load_dwordx4 v131, s[12:15], s59 offen lds
	ds_read_b128 v[172:175], v133 offset:32768
	ds_read_b128 v[176:179], v133 offset:33792
	ds_read_b128 v[180:183], v133 offset:34816
	ds_read_b128 v[184:187], v133 offset:35840
	ds_read_b128 v[188:191], v133 offset:36864
	ds_read_b128 v[192:195], v133 offset:37888
	ds_read_b128 v[196:199], v133 offset:38912
	ds_read_b128 v[200:203], v133 offset:39936
	s_waitcnt vmcnt(8)
	s_waitcnt lgkmcnt(0)
	s_barrier
	s_setprio 1
	s_waitcnt lgkmcnt(7)
	v_mfma_f32_16x16x32_bf16 v[134:137], v[138:141], v[172:175], v[134:137]
	v_mfma_f32_16x16x32_bf16 v[122:125], v[148:151], v[172:175], v[122:125]
	s_waitcnt lgkmcnt(5)
	v_mfma_f32_16x16x32_bf16 v[110:113], v[138:141], v[180:183], v[110:113]
	v_mfma_f32_16x16x32_bf16 v[106:109], v[148:151], v[180:183], v[106:109]
	s_waitcnt lgkmcnt(3)
	v_mfma_f32_16x16x32_bf16 v[94:97], v[138:141], v[188:191], v[94:97]
	v_mfma_f32_16x16x32_bf16 v[90:93], v[148:151], v[188:191], v[90:93]
	s_waitcnt lgkmcnt(1)
	v_mfma_f32_16x16x32_bf16 v[78:81], v[138:141], v[196:199], v[78:81]
	v_mfma_f32_16x16x32_bf16 v[74:77], v[148:151], v[196:199], v[74:77]
	v_mfma_f32_16x16x32_bf16 v[134:137], v[142:145], v[176:179], v[134:137]
	v_mfma_f32_16x16x32_bf16 v[122:125], v[152:155], v[176:179], v[122:125]
	v_mfma_f32_16x16x32_bf16 v[110:113], v[142:145], v[184:187], v[110:113]
	v_mfma_f32_16x16x32_bf16 v[106:109], v[152:155], v[184:187], v[106:109]
	v_mfma_f32_16x16x32_bf16 v[94:97], v[142:145], v[192:195], v[94:97]
	v_mfma_f32_16x16x32_bf16 v[90:93], v[152:155], v[192:195], v[90:93]
	s_waitcnt lgkmcnt(0)
	v_mfma_f32_16x16x32_bf16 v[78:81], v[142:145], v[200:203], v[78:81]
	v_mfma_f32_16x16x32_bf16 v[74:77], v[152:155], v[200:203], v[74:77]
	s_setprio 0
	s_setprio 1
	v_mfma_f32_16x16x32_bf16 v[118:121], v[156:159], v[172:175], v[118:121]
	v_mfma_f32_16x16x32_bf16 v[114:117], v[164:167], v[172:175], v[114:117]
	v_mfma_f32_16x16x32_bf16 v[102:105], v[156:159], v[180:183], v[102:105]
	v_mfma_f32_16x16x32_bf16 v[98:101], v[164:167], v[180:183], v[98:101]
	v_mfma_f32_16x16x32_bf16 v[86:89], v[156:159], v[188:191], v[86:89]
	v_mfma_f32_16x16x32_bf16 v[82:85], v[164:167], v[188:191], v[82:85]
	v_mfma_f32_16x16x32_bf16 v[70:73], v[156:159], v[196:199], v[70:73]
	v_mfma_f32_16x16x32_bf16 v[66:69], v[164:167], v[196:199], v[66:69]
	v_mfma_f32_16x16x32_bf16 v[118:121], v[160:163], v[176:179], v[118:121]
	v_mfma_f32_16x16x32_bf16 v[114:117], v[168:171], v[176:179], v[114:117]
	v_mfma_f32_16x16x32_bf16 v[102:105], v[160:163], v[184:187], v[102:105]
	v_mfma_f32_16x16x32_bf16 v[98:101], v[168:171], v[184:187], v[98:101]
	v_mfma_f32_16x16x32_bf16 v[86:89], v[160:163], v[192:195], v[86:89]
	v_mfma_f32_16x16x32_bf16 v[82:85], v[168:171], v[192:195], v[82:85]
	v_mfma_f32_16x16x32_bf16 v[70:73], v[160:163], v[200:203], v[70:73]
	v_mfma_f32_16x16x32_bf16 v[66:69], v[168:171], v[200:203], v[66:69]
	s_setprio 0
	s_barrier
	ds_read_b128 v[172:175], v133 offset:49152
	ds_read_b128 v[176:179], v133 offset:50176
	s_add_i32 s59, s58, 0x80
	s_mov_b32 m0, s40
	s_nop 0
	buffer_load_dwordx4 v130, s[8:11], s59 offen lds
	ds_read_b128 v[180:183], v133 offset:51200
	ds_read_b128 v[184:187], v133 offset:52224
	s_add_i32 s58, s58, 0xb0080
	s_mov_b32 m0, s41
	s_nop 0
	buffer_load_dwordx4 v131, s[8:11], s59 offen lds
	ds_read_b128 v[188:191], v133 offset:53248
	ds_read_b128 v[192:195], v133 offset:54272
	s_nop 0
	s_mov_b32 m0, s44
	s_nop 0
	buffer_load_dwordx4 v130, s[8:11], s58 offen lds
	ds_read_b128 v[196:199], v133 offset:55296
	ds_read_b128 v[200:203], v133 offset:56320
	s_nop 0
	s_mov_b32 m0, s45
	s_nop 0
	buffer_load_dwordx4 v131, s[8:11], s58 offen lds
	s_nop 0
	s_mov_b32 m0, s42
	s_nop 0
	buffer_load_dwordx4 v130, s[12:15], s55 offen lds
	s_nop 0
	s_mov_b32 m0, s43
	s_nop 0
	buffer_load_dwordx4 v131, s[12:15], s55 offen lds
	s_waitcnt vmcnt(8)
	s_waitcnt lgkmcnt(0)
	s_barrier
	s_setprio 1
	s_waitcnt lgkmcnt(7)
	v_mfma_f32_16x16x32_bf16 v[62:65], v[138:141], v[172:175], v[62:65]
	v_mfma_f32_16x16x32_bf16 v[58:61], v[148:151], v[172:175], v[58:61]
	s_waitcnt lgkmcnt(5)
	v_mfma_f32_16x16x32_bf16 v[46:49], v[138:141], v[180:183], v[46:49]
	v_mfma_f32_16x16x32_bf16 v[42:45], v[148:151], v[180:183], v[42:45]
	s_waitcnt lgkmcnt(3)
	v_mfma_f32_16x16x32_bf16 v[30:33], v[138:141], v[188:191], v[30:33]
	v_mfma_f32_16x16x32_bf16 v[26:29], v[148:151], v[188:191], v[26:29]
	s_waitcnt lgkmcnt(1)
	v_mfma_f32_16x16x32_bf16 v[14:17], v[138:141], v[196:199], v[14:17]
	v_mfma_f32_16x16x32_bf16 v[10:13], v[148:151], v[196:199], v[10:13]
	v_mfma_f32_16x16x32_bf16 v[62:65], v[142:145], v[176:179], v[62:65]
	v_mfma_f32_16x16x32_bf16 v[58:61], v[152:155], v[176:179], v[58:61]
	v_mfma_f32_16x16x32_bf16 v[46:49], v[142:145], v[184:187], v[46:49]
	v_mfma_f32_16x16x32_bf16 v[42:45], v[152:155], v[184:187], v[42:45]
	v_mfma_f32_16x16x32_bf16 v[30:33], v[142:145], v[192:195], v[30:33]
	v_mfma_f32_16x16x32_bf16 v[26:29], v[152:155], v[192:195], v[26:29]
	s_waitcnt lgkmcnt(0)
	v_mfma_f32_16x16x32_bf16 v[14:17], v[142:145], v[200:203], v[14:17]
	v_mfma_f32_16x16x32_bf16 v[10:13], v[152:155], v[200:203], v[10:13]
	s_setprio 0
	s_setprio 1
	v_mfma_f32_16x16x32_bf16 v[54:57], v[156:159], v[172:175], v[54:57]
	v_mfma_f32_16x16x32_bf16 v[50:53], v[164:167], v[172:175], v[50:53]
	v_mfma_f32_16x16x32_bf16 v[38:41], v[156:159], v[180:183], v[38:41]
	v_mfma_f32_16x16x32_bf16 v[34:37], v[164:167], v[180:183], v[34:37]
	v_mfma_f32_16x16x32_bf16 v[22:25], v[156:159], v[188:191], v[22:25]
	v_mfma_f32_16x16x32_bf16 v[18:21], v[164:167], v[188:191], v[18:21]
	v_mfma_f32_16x16x32_bf16 v[6:9], v[156:159], v[196:199], v[6:9]
	v_mfma_f32_16x16x32_bf16 v[2:5], v[164:167], v[196:199], v[2:5]
	v_mfma_f32_16x16x32_bf16 v[54:57], v[160:163], v[176:179], v[54:57]
	v_mfma_f32_16x16x32_bf16 v[50:53], v[168:171], v[176:179], v[50:53]
	v_mfma_f32_16x16x32_bf16 v[38:41], v[160:163], v[184:187], v[38:41]
	v_mfma_f32_16x16x32_bf16 v[34:37], v[168:171], v[184:187], v[34:37]
	v_mfma_f32_16x16x32_bf16 v[22:25], v[160:163], v[192:195], v[22:25]
	v_mfma_f32_16x16x32_bf16 v[18:21], v[168:171], v[192:195], v[18:21]
	v_mfma_f32_16x16x32_bf16 v[6:9], v[160:163], v[200:203], v[6:9]
	v_mfma_f32_16x16x32_bf16 v[2:5], v[168:171], v[200:203], v[2:5]
	s_setprio 0
	s_add_i32 s0, s0, 2
	s_addk_i32 s1, 0x100
	s_cmp_gt_u32 s0, 41
	s_barrier
	s_cbranch_scc0 .LBB0_467
	s_andn2_b64 vcc, exec, s[6:7]
	s_cbranch_vccnz .LBB0_455
	v_mov_b32_e32 v2, 0
	s_mov_b32 s18, s50
	s_mov_b32 s31, s51
	s_mov_b32 s33, s54
	s_mov_b32 s3, s53
	s_mov_b32 s49, s52
	v_mov_b32_e32 v3, v2
	v_mov_b32_e32 v4, v2
	v_mov_b32_e32 v5, v2
	v_mov_b32_e32 v6, v2
	v_mov_b32_e32 v7, v2
	v_mov_b32_e32 v8, v2
	v_mov_b32_e32 v9, v2
	v_mov_b32_e32 v18, v2
	v_mov_b32_e32 v19, v2
	v_mov_b32_e32 v20, v2
	v_mov_b32_e32 v21, v2
	v_mov_b32_e32 v22, v2
	v_mov_b32_e32 v23, v2
	v_mov_b32_e32 v24, v2
	v_mov_b32_e32 v25, v2
	v_mov_b32_e32 v34, v2
	v_mov_b32_e32 v35, v2
	v_mov_b32_e32 v36, v2
	v_mov_b32_e32 v37, v2
	v_mov_b32_e32 v38, v2
	v_mov_b32_e32 v39, v2
	v_mov_b32_e32 v40, v2
	v_mov_b32_e32 v41, v2
	v_mov_b32_e32 v50, v2
	v_mov_b32_e32 v51, v2
	v_mov_b32_e32 v52, v2
	v_mov_b32_e32 v53, v2
	v_mov_b32_e32 v54, v2
	v_mov_b32_e32 v55, v2
	v_mov_b32_e32 v56, v2
	v_mov_b32_e32 v57, v2
	v_mov_b32_e32 v10, v2
	v_mov_b32_e32 v11, v2
	v_mov_b32_e32 v12, v2
	v_mov_b32_e32 v13, v2
	v_mov_b32_e32 v14, v2
	v_mov_b32_e32 v15, v2
	v_mov_b32_e32 v16, v2
	v_mov_b32_e32 v17, v2
	v_mov_b32_e32 v26, v2
	v_mov_b32_e32 v27, v2
	v_mov_b32_e32 v28, v2
	v_mov_b32_e32 v29, v2
	v_mov_b32_e32 v30, v2
	v_mov_b32_e32 v31, v2
	v_mov_b32_e32 v32, v2
	v_mov_b32_e32 v33, v2
	v_mov_b32_e32 v42, v2
	v_mov_b32_e32 v43, v2
	v_mov_b32_e32 v44, v2
	v_mov_b32_e32 v45, v2
	v_mov_b32_e32 v46, v2
	v_mov_b32_e32 v47, v2
	v_mov_b32_e32 v48, v2
	v_mov_b32_e32 v49, v2
	v_mov_b32_e32 v58, v2
	v_mov_b32_e32 v59, v2
	v_mov_b32_e32 v60, v2
	v_mov_b32_e32 v61, v2
	v_mov_b32_e32 v62, v2
	v_mov_b32_e32 v63, v2
	v_mov_b32_e32 v64, v2
	v_mov_b32_e32 v65, v2
	v_mov_b32_e32 v66, v2
	v_mov_b32_e32 v67, v2
	v_mov_b32_e32 v68, v2
	v_mov_b32_e32 v69, v2
	v_mov_b32_e32 v70, v2
	v_mov_b32_e32 v71, v2
	v_mov_b32_e32 v72, v2
	v_mov_b32_e32 v73, v2
	v_mov_b32_e32 v82, v2
	v_mov_b32_e32 v83, v2
	v_mov_b32_e32 v84, v2
	v_mov_b32_e32 v85, v2
	v_mov_b32_e32 v86, v2
	v_mov_b32_e32 v87, v2
	v_mov_b32_e32 v88, v2
	v_mov_b32_e32 v89, v2
	v_mov_b32_e32 v98, v2
	v_mov_b32_e32 v99, v2
	v_mov_b32_e32 v100, v2
	v_mov_b32_e32 v101, v2
	v_mov_b32_e32 v102, v2
	v_mov_b32_e32 v103, v2
	v_mov_b32_e32 v104, v2
	v_mov_b32_e32 v105, v2
	v_mov_b32_e32 v114, v2
	v_mov_b32_e32 v115, v2
	v_mov_b32_e32 v116, v2
	v_mov_b32_e32 v117, v2
	v_mov_b32_e32 v118, v2
	v_mov_b32_e32 v119, v2
	v_mov_b32_e32 v120, v2
	v_mov_b32_e32 v121, v2
	v_mov_b32_e32 v74, v2
	v_mov_b32_e32 v75, v2
	v_mov_b32_e32 v76, v2
	v_mov_b32_e32 v77, v2
	v_mov_b32_e32 v78, v2
	v_mov_b32_e32 v79, v2
	v_mov_b32_e32 v80, v2
	v_mov_b32_e32 v81, v2
	v_mov_b32_e32 v90, v2
	v_mov_b32_e32 v91, v2
	v_mov_b32_e32 v92, v2
	v_mov_b32_e32 v93, v2
	v_mov_b32_e32 v94, v2
	v_mov_b32_e32 v95, v2
	v_mov_b32_e32 v96, v2
	v_mov_b32_e32 v97, v2
	v_mov_b32_e32 v106, v2
	v_mov_b32_e32 v107, v2
	v_mov_b32_e32 v108, v2
	v_mov_b32_e32 v109, v2
	v_mov_b32_e32 v110, v2
	v_mov_b32_e32 v111, v2
	v_mov_b32_e32 v112, v2
	v_mov_b32_e32 v113, v2
	v_mov_b32_e32 v122, v2
	v_mov_b32_e32 v123, v2
	v_mov_b32_e32 v124, v2
	v_mov_b32_e32 v125, v2
	v_mov_b32_e32 v134, v2
	v_mov_b32_e32 v135, v2
	v_mov_b32_e32 v136, v2
	v_mov_b32_e32 v137, v2
	s_branch .LBB0_455

.LBB0_619:
	ds_read_b128 v[38:41], v210
	ds_read_b128 v[42:45], v210 offset:1024
	ds_read_b128 v[46:49], v210 offset:2048
	ds_read_b128 v[58:61], v210 offset:3072
	ds_read_b128 v[142:145], v211
	ds_read_b128 v[146:149], v211 offset:1024
	ds_read_b128 v[150:153], v211 offset:2048
	ds_read_b128 v[154:157], v211 offset:3072
	s_add_i32 s6, s1, 0xfffe0080
	s_cmp_eq_u32 s3, 4
	s_cselect_b32 s8, s75, s6
	s_cselect_b32 s7, s0, s2
	s_add_i32 s6, s8, 0x80
	s_mov_b32 m0, s68
	s_nop 0
	buffer_load_dwordx4 v206, s[16:19], s1 offen lds
	s_nop 0
	s_mov_b32 m0, s69
	s_nop 0
	buffer_load_dwordx4 v207, s[16:19], s1 offen lds
	ds_read_b128 v[166:169], v212
	ds_read_b128 v[170:173], v212 offset:1024
	ds_read_b128 v[174:177], v212 offset:2048
	ds_read_b128 v[178:181], v212 offset:3072
	ds_read_b128 v[190:193], v212 offset:4096
	ds_read_b128 v[194:197], v212 offset:5120
	ds_read_b128 v[198:201], v212 offset:6144
	ds_read_b128 v[216:219], v212 offset:7168
	s_waitcnt vmcnt(8)
	s_waitcnt lgkmcnt(0)
	s_barrier
	s_setprio 1
	s_waitcnt lgkmcnt(7)
	v_mfma_i32_16x16x64_i8 v[162:165], v[38:41], v[166:169], v[162:165]
	v_mfma_i32_16x16x64_i8 v[158:161], v[46:49], v[166:169], v[158:161]
	s_waitcnt lgkmcnt(5)
	v_mfma_i32_16x16x64_i8 v[130:133], v[38:41], v[174:177], v[130:133]
	v_mfma_i32_16x16x64_i8 v[126:129], v[46:49], v[174:177], v[126:129]
	s_waitcnt lgkmcnt(3)
	v_mfma_i32_16x16x64_i8 v[114:117], v[38:41], v[190:193], v[114:117]
	v_mfma_i32_16x16x64_i8 v[110:113], v[46:49], v[190:193], v[110:113]
	s_waitcnt lgkmcnt(1)
	v_mfma_i32_16x16x64_i8 v[98:101], v[38:41], v[198:201], v[98:101]
	v_mfma_i32_16x16x64_i8 v[94:97], v[46:49], v[198:201], v[94:97]
	v_mfma_i32_16x16x64_i8 v[162:165], v[42:45], v[170:173], v[162:165]
	v_mfma_i32_16x16x64_i8 v[158:161], v[58:61], v[170:173], v[158:161]
	v_mfma_i32_16x16x64_i8 v[130:133], v[42:45], v[178:181], v[130:133]
	v_mfma_i32_16x16x64_i8 v[126:129], v[58:61], v[178:181], v[126:129]
	v_mfma_i32_16x16x64_i8 v[114:117], v[42:45], v[194:197], v[114:117]
	v_mfma_i32_16x16x64_i8 v[110:113], v[58:61], v[194:197], v[110:113]
	s_waitcnt lgkmcnt(0)
	v_mfma_i32_16x16x64_i8 v[98:101], v[42:45], v[216:219], v[98:101]
	v_mfma_i32_16x16x64_i8 v[94:97], v[58:61], v[216:219], v[94:97]
	s_setprio 0
	s_setprio 1
	v_mfma_i32_16x16x64_i8 v[138:141], v[142:145], v[166:169], v[138:141]
	v_mfma_i32_16x16x64_i8 v[134:137], v[150:153], v[166:169], v[134:137]
	v_mfma_i32_16x16x64_i8 v[122:125], v[142:145], v[174:177], v[122:125]
	v_mfma_i32_16x16x64_i8 v[118:121], v[150:153], v[174:177], v[118:121]
	v_mfma_i32_16x16x64_i8 v[106:109], v[142:145], v[190:193], v[106:109]
	v_mfma_i32_16x16x64_i8 v[102:105], v[150:153], v[190:193], v[102:105]
	v_mfma_i32_16x16x64_i8 v[90:93], v[142:145], v[198:201], v[90:93]
	v_mfma_i32_16x16x64_i8 v[86:89], v[150:153], v[198:201], v[86:89]
	v_mfma_i32_16x16x64_i8 v[138:141], v[146:149], v[170:173], v[138:141]
	v_mfma_i32_16x16x64_i8 v[134:137], v[154:157], v[170:173], v[134:137]
	v_mfma_i32_16x16x64_i8 v[122:125], v[146:149], v[178:181], v[122:125]
	v_mfma_i32_16x16x64_i8 v[118:121], v[154:157], v[178:181], v[118:121]
	v_mfma_i32_16x16x64_i8 v[106:109], v[146:149], v[194:197], v[106:109]
	v_mfma_i32_16x16x64_i8 v[102:105], v[154:157], v[194:197], v[102:105]
	v_mfma_i32_16x16x64_i8 v[90:93], v[146:149], v[216:219], v[90:93]
	v_mfma_i32_16x16x64_i8 v[86:89], v[154:157], v[216:219], v[86:89]
	s_setprio 0
	s_barrier
	ds_read_b128 v[166:169], v212 offset:16384
	ds_read_b128 v[170:173], v212 offset:17408
	s_mov_b32 m0, s48
	s_nop 0
	buffer_load_dwordx4 v204, s[12:15], s7 offen lds
	ds_read_b128 v[174:177], v212 offset:18432
	ds_read_b128 v[178:181], v212 offset:19456
	s_add_i32 s9, s7, 0x20000
	s_mov_b32 m0, s49
	s_nop 0
	buffer_load_dwordx4 v205, s[12:15], s7 offen lds
	ds_read_b128 v[190:193], v212 offset:20480
	ds_read_b128 v[194:197], v212 offset:21504
	s_nop 0
	s_mov_b32 m0, s50
	s_nop 0
	buffer_load_dwordx4 v204, s[12:15], s9 offen lds
	ds_read_b128 v[198:201], v212 offset:22528
	ds_read_b128 v[216:219], v212 offset:23552
	s_nop 0
	s_mov_b32 m0, s51
	s_nop 0
	buffer_load_dwordx4 v205, s[12:15], s9 offen lds
	s_nop 0
	s_mov_b32 m0, s47
	s_nop 0
	buffer_load_dwordx4 v206, s[16:19], s8 offen lds
	s_nop 0
	s_mov_b32 m0, s52
	s_nop 0
	buffer_load_dwordx4 v207, s[16:19], s8 offen lds
	s_waitcnt vmcnt(8)
	s_waitcnt lgkmcnt(0)
	s_barrier
	s_setprio 1
	s_waitcnt lgkmcnt(7)
	v_mfma_i32_16x16x64_i8 v[82:85], v[38:41], v[166:169], v[82:85]
	v_mfma_i32_16x16x64_i8 v[78:81], v[46:49], v[166:169], v[78:81]
	s_waitcnt lgkmcnt(5)
	v_mfma_i32_16x16x64_i8 v[66:69], v[38:41], v[174:177], v[66:69]
	v_mfma_i32_16x16x64_i8 v[62:65], v[46:49], v[174:177], v[62:65]
	s_waitcnt lgkmcnt(3)
	v_mfma_i32_16x16x64_i8 v[34:37], v[38:41], v[190:193], v[34:37]
	v_mfma_i32_16x16x64_i8 v[30:33], v[46:49], v[190:193], v[30:33]
	s_waitcnt lgkmcnt(1)
	v_mfma_i32_16x16x64_i8 v[18:21], v[38:41], v[198:201], v[18:21]
	v_mfma_i32_16x16x64_i8 v[14:17], v[46:49], v[198:201], v[14:17]
	v_mfma_i32_16x16x64_i8 v[82:85], v[42:45], v[170:173], v[82:85]
	v_mfma_i32_16x16x64_i8 v[78:81], v[58:61], v[170:173], v[78:81]
	v_mfma_i32_16x16x64_i8 v[66:69], v[42:45], v[178:181], v[66:69]
	v_mfma_i32_16x16x64_i8 v[62:65], v[58:61], v[178:181], v[62:65]
	v_mfma_i32_16x16x64_i8 v[34:37], v[42:45], v[194:197], v[34:37]
	v_mfma_i32_16x16x64_i8 v[30:33], v[58:61], v[194:197], v[30:33]
	s_waitcnt lgkmcnt(0)
	v_mfma_i32_16x16x64_i8 v[18:21], v[42:45], v[216:219], v[18:21]
	v_mfma_i32_16x16x64_i8 v[14:17], v[58:61], v[216:219], v[14:17]
	s_setprio 0
	s_setprio 1
	v_mfma_i32_16x16x64_i8 v[50:53], v[150:153], v[174:177], v[50:53]
	v_mfma_i32_16x16x64_i8 v[26:29], v[142:145], v[190:193], v[26:29]
	v_mfma_i32_16x16x64_i8 v[22:25], v[150:153], v[190:193], v[22:25]
	v_mfma_i32_16x16x64_i8 v[10:13], v[142:145], v[198:201], v[10:13]
	v_mfma_i32_16x16x64_i8 v[4:7], v[150:153], v[198:201], v[6:9]
	v_mfma_i32_16x16x64_i8 v[38:41], v[142:145], v[166:169], v[74:77]
	v_mfma_i32_16x16x64_i8 v[42:45], v[150:153], v[166:169], v[70:73]
	v_mfma_i32_16x16x64_i8 v[46:49], v[142:145], v[174:177], v[54:57]
	v_mfma_i32_16x16x64_i8 v[50:53], v[154:157], v[178:181], v[50:53]
	v_mfma_i32_16x16x64_i8 v[26:29], v[146:149], v[194:197], v[26:29]
	v_mfma_i32_16x16x64_i8 v[22:25], v[154:157], v[194:197], v[22:25]
	v_mfma_i32_16x16x64_i8 v[10:13], v[146:149], v[216:219], v[10:13]
	v_mfma_i32_16x16x64_i8 v[4:7], v[154:157], v[216:219], v[4:7]
	v_mfma_i32_16x16x64_i8 v[38:41], v[146:149], v[170:173], v[38:41]
	v_mfma_i32_16x16x64_i8 v[42:45], v[154:157], v[170:173], v[42:45]
	v_mfma_i32_16x16x64_i8 v[46:49], v[146:149], v[178:181], v[46:49]
	s_setprio 0
	s_barrier
	ds_read_b128 v[54:57], v213
	ds_read_b128 v[58:61], v213 offset:1024
	ds_read_b128 v[70:73], v213 offset:2048
	ds_read_b128 v[74:77], v213 offset:3072
	ds_read_b128 v[142:145], v214
	ds_read_b128 v[146:149], v214 offset:1024
	ds_read_b128 v[150:153], v214 offset:2048
	ds_read_b128 v[154:157], v214 offset:3072
	s_add_i32 s8, s8, 0x20000
	s_mov_b32 m0, s53
	s_nop 0
	buffer_load_dwordx4 v206, s[16:19], s8 offen lds
	s_nop 0
	s_mov_b32 m0, s54
	s_nop 0
	buffer_load_dwordx4 v207, s[16:19], s8 offen lds
	ds_read_b128 v[166:169], v212 offset:32768
	ds_read_b128 v[170:173], v212 offset:33792
	ds_read_b128 v[174:177], v212 offset:34816
	ds_read_b128 v[178:181], v212 offset:35840
	ds_read_b128 v[190:193], v212 offset:36864
	ds_read_b128 v[194:197], v212 offset:37888
	ds_read_b128 v[198:201], v212 offset:38912
	ds_read_b128 v[216:219], v212 offset:39936
	s_waitcnt vmcnt(8)
	s_waitcnt lgkmcnt(0)
	s_barrier
	s_setprio 1
	s_waitcnt lgkmcnt(7)
	v_mfma_i32_16x16x64_i8 v[162:165], v[54:57], v[166:169], v[162:165]
	v_mfma_i32_16x16x64_i8 v[158:161], v[70:73], v[166:169], v[158:161]
	s_waitcnt lgkmcnt(5)
	v_mfma_i32_16x16x64_i8 v[130:133], v[54:57], v[174:177], v[130:133]
	v_mfma_i32_16x16x64_i8 v[126:129], v[70:73], v[174:177], v[126:129]
	s_waitcnt lgkmcnt(3)
	v_mfma_i32_16x16x64_i8 v[114:117], v[54:57], v[190:193], v[114:117]
	v_mfma_i32_16x16x64_i8 v[110:113], v[70:73], v[190:193], v[110:113]
	s_waitcnt lgkmcnt(1)
	v_mfma_i32_16x16x64_i8 v[98:101], v[54:57], v[198:201], v[98:101]
	v_mfma_i32_16x16x64_i8 v[94:97], v[70:73], v[198:201], v[94:97]
	v_mfma_i32_16x16x64_i8 v[162:165], v[58:61], v[170:173], v[162:165]
	v_mfma_i32_16x16x64_i8 v[158:161], v[74:77], v[170:173], v[158:161]
	v_mfma_i32_16x16x64_i8 v[130:133], v[58:61], v[178:181], v[130:133]
	v_mfma_i32_16x16x64_i8 v[126:129], v[74:77], v[178:181], v[126:129]
	v_mfma_i32_16x16x64_i8 v[114:117], v[58:61], v[194:197], v[114:117]
	v_mfma_i32_16x16x64_i8 v[110:113], v[74:77], v[194:197], v[110:113]
	s_waitcnt lgkmcnt(0)
	v_mfma_i32_16x16x64_i8 v[98:101], v[58:61], v[216:219], v[98:101]
	v_mfma_i32_16x16x64_i8 v[94:97], v[74:77], v[216:219], v[94:97]
	s_setprio 0
	s_setprio 1
	v_mfma_i32_16x16x64_i8 v[138:141], v[142:145], v[166:169], v[138:141]
	v_mfma_i32_16x16x64_i8 v[134:137], v[150:153], v[166:169], v[134:137]
	v_mfma_i32_16x16x64_i8 v[122:125], v[142:145], v[174:177], v[122:125]
	v_mfma_i32_16x16x64_i8 v[118:121], v[150:153], v[174:177], v[118:121]
	v_mfma_i32_16x16x64_i8 v[106:109], v[142:145], v[190:193], v[106:109]
	v_mfma_i32_16x16x64_i8 v[102:105], v[150:153], v[190:193], v[102:105]
	v_mfma_i32_16x16x64_i8 v[90:93], v[142:145], v[198:201], v[90:93]
	v_mfma_i32_16x16x64_i8 v[86:89], v[150:153], v[198:201], v[86:89]
	v_mfma_i32_16x16x64_i8 v[138:141], v[146:149], v[170:173], v[138:141]
	v_mfma_i32_16x16x64_i8 v[134:137], v[154:157], v[170:173], v[134:137]
	v_mfma_i32_16x16x64_i8 v[122:125], v[146:149], v[178:181], v[122:125]
	v_mfma_i32_16x16x64_i8 v[118:121], v[154:157], v[178:181], v[118:121]
	v_mfma_i32_16x16x64_i8 v[106:109], v[146:149], v[194:197], v[106:109]
	v_mfma_i32_16x16x64_i8 v[102:105], v[154:157], v[194:197], v[102:105]
	v_mfma_i32_16x16x64_i8 v[90:93], v[146:149], v[216:219], v[90:93]
	v_mfma_i32_16x16x64_i8 v[86:89], v[154:157], v[216:219], v[86:89]
	s_setprio 0
	s_barrier
	ds_read_b128 v[166:169], v212 offset:49152
	ds_read_b128 v[170:173], v212 offset:50176
	s_or_b32 s8, s7, 0x80
	s_mov_b32 m0, s62
	s_nop 0
	buffer_load_dwordx4 v204, s[12:15], s8 offen lds
	ds_read_b128 v[174:177], v212 offset:51200
	ds_read_b128 v[178:181], v212 offset:52224
	s_add_i32 s7, s7, 0x20080
	s_mov_b32 m0, s63
	s_nop 0
	buffer_load_dwordx4 v205, s[12:15], s8 offen lds
	ds_read_b128 v[190:193], v212 offset:53248
	ds_read_b128 v[194:197], v212 offset:54272
	s_nop 0
	s_mov_b32 m0, s66
	s_nop 0
	buffer_load_dwordx4 v204, s[12:15], s7 offen lds
	ds_read_b128 v[198:201], v212 offset:55296
	ds_read_b128 v[216:219], v212 offset:56320
	s_nop 0
	s_mov_b32 m0, s67
	s_nop 0
	buffer_load_dwordx4 v205, s[12:15], s7 offen lds
	s_nop 0
	s_mov_b32 m0, s64
	s_nop 0
	buffer_load_dwordx4 v206, s[16:19], s6 offen lds
	s_nop 0
	s_mov_b32 m0, s65
	s_nop 0
	buffer_load_dwordx4 v207, s[16:19], s6 offen lds
	s_waitcnt vmcnt(8)
	s_waitcnt lgkmcnt(0)
	s_barrier
	s_setprio 1
	s_waitcnt lgkmcnt(7)
	v_mfma_i32_16x16x64_i8 v[82:85], v[54:57], v[166:169], v[82:85]
	v_mfma_i32_16x16x64_i8 v[78:81], v[70:73], v[166:169], v[78:81]
	s_waitcnt lgkmcnt(5)
	v_mfma_i32_16x16x64_i8 v[66:69], v[54:57], v[174:177], v[66:69]
	v_mfma_i32_16x16x64_i8 v[62:65], v[70:73], v[174:177], v[62:65]
	s_waitcnt lgkmcnt(3)
	v_mfma_i32_16x16x64_i8 v[34:37], v[54:57], v[190:193], v[34:37]
	v_mfma_i32_16x16x64_i8 v[30:33], v[70:73], v[190:193], v[30:33]
	s_waitcnt lgkmcnt(1)
	v_mfma_i32_16x16x64_i8 v[18:21], v[54:57], v[198:201], v[18:21]
	v_mfma_i32_16x16x64_i8 v[14:17], v[70:73], v[198:201], v[14:17]
	v_mfma_i32_16x16x64_i8 v[82:85], v[58:61], v[170:173], v[82:85]
	v_mfma_i32_16x16x64_i8 v[78:81], v[74:77], v[170:173], v[78:81]
	v_mfma_i32_16x16x64_i8 v[66:69], v[58:61], v[178:181], v[66:69]
	v_mfma_i32_16x16x64_i8 v[62:65], v[74:77], v[178:181], v[62:65]
	v_mfma_i32_16x16x64_i8 v[34:37], v[58:61], v[194:197], v[34:37]
	v_mfma_i32_16x16x64_i8 v[30:33], v[74:77], v[194:197], v[30:33]
	s_waitcnt lgkmcnt(0)
	v_mfma_i32_16x16x64_i8 v[18:21], v[58:61], v[216:219], v[18:21]
	v_mfma_i32_16x16x64_i8 v[14:17], v[74:77], v[216:219], v[14:17]
	s_setprio 0
	s_setprio 1
	v_mfma_i32_16x16x64_i8 v[38:41], v[142:145], v[166:169], v[38:41]
	v_mfma_i32_16x16x64_i8 v[74:77], v[146:149], v[170:173], v[38:41]
	v_mfma_i32_16x16x64_i8 v[38:41], v[150:153], v[166:169], v[42:45]
	v_mfma_i32_16x16x64_i8 v[70:73], v[154:157], v[170:173], v[38:41]
	v_mfma_i32_16x16x64_i8 v[38:41], v[142:145], v[174:177], v[46:49]
	v_mfma_i32_16x16x64_i8 v[54:57], v[146:149], v[178:181], v[38:41]
	v_mfma_i32_16x16x64_i8 v[38:41], v[150:153], v[174:177], v[50:53]
	v_mfma_i32_16x16x64_i8 v[26:29], v[142:145], v[190:193], v[26:29]
	v_mfma_i32_16x16x64_i8 v[22:25], v[150:153], v[190:193], v[22:25]
	v_mfma_i32_16x16x64_i8 v[8:11], v[142:145], v[198:201], v[10:13]
	v_mfma_i32_16x16x64_i8 v[4:7], v[150:153], v[198:201], v[4:7]
	v_mfma_i32_16x16x64_i8 v[50:53], v[154:157], v[178:181], v[38:41]
	v_mfma_i32_16x16x64_i8 v[26:29], v[146:149], v[194:197], v[26:29]
	v_mfma_i32_16x16x64_i8 v[22:25], v[154:157], v[194:197], v[22:25]
	v_mfma_i32_16x16x64_i8 v[10:13], v[146:149], v[216:219], v[8:11]
	v_mfma_i32_16x16x64_i8 v[6:9], v[154:157], v[216:219], v[4:7]
	s_setprio 0
	s_add_i32 s3, s3, 2
	s_addk_i32 s1, 0x100
	s_addk_i32 s2, 0x100
	s_cmp_gt_u32 s3, 5
	s_barrier
	s_cbranch_scc0 .LBB0_619
	s_and_b64 vcc, exec, s[34:35]
	s_cbranch_vccz .LBB0_622
	s_barrier

.LBB0_943:
	v_add_u32_e32 v150, 0x10000, v8
	v_add_u32_e32 v166, 0x14000, v8
	ds_read_b128 v[10:13], v150
	ds_read_b128 v[14:17], v150 offset:1024
	ds_read_b128 v[146:149], v150 offset:2048
	ds_read_b128 v[150:153], v150 offset:3072
	ds_read_b128 v[154:157], v166
	ds_read_b128 v[158:161], v166 offset:1024
	ds_read_b128 v[162:165], v166 offset:2048
	ds_read_b128 v[166:169], v166 offset:3072
	s_add_i32 s61, s37, s58
	s_add_i32 s60, s33, s58
	s_add_i32 s59, s61, 0x400
	s_addk_i32 s60, 0x400
	s_cmp_eq_u32 s58, 0
	s_cselect_b32 s62, s53, s59
	s_cselect_b32 s60, s54, s60
	s_or_b32 s59, s62, 0x80
	s_add_i32 s61, s61, 0x20380
	s_mov_b32 m0, s48
	s_nop 0
	buffer_load_dwordx4 v6, s[12:15], s61 offen lds
	s_nop 0
	s_mov_b32 m0, s49
	s_nop 0
	buffer_load_dwordx4 v7, s[12:15], s61 offen lds
	ds_read_b128 v[170:173], v9
	ds_read_b128 v[174:177], v9 offset:1024
	ds_read_b128 v[178:181], v9 offset:2048
	ds_read_b128 v[182:185], v9 offset:3072
	ds_read_b128 v[186:189], v9 offset:4096
	ds_read_b128 v[190:193], v9 offset:5120
	ds_read_b128 v[194:197], v9 offset:6144
	ds_read_b128 v[198:201], v9 offset:7168
	s_waitcnt vmcnt(8)
	s_waitcnt lgkmcnt(0)
	s_barrier
	s_setprio 1
	s_waitcnt lgkmcnt(7)
	v_mfma_i32_16x16x64_i8 v[142:145], v[10:13], v[170:173], v[142:145]
	v_mfma_i32_16x16x64_i8 v[138:141], v[146:149], v[170:173], v[138:141]
	s_waitcnt lgkmcnt(5)
	v_mfma_i32_16x16x64_i8 v[126:129], v[10:13], v[178:181], v[126:129]
	v_mfma_i32_16x16x64_i8 v[122:125], v[146:149], v[178:181], v[122:125]
	s_waitcnt lgkmcnt(3)
	v_mfma_i32_16x16x64_i8 v[110:113], v[10:13], v[186:189], v[110:113]
	v_mfma_i32_16x16x64_i8 v[106:109], v[146:149], v[186:189], v[106:109]
	s_waitcnt lgkmcnt(1)
	v_mfma_i32_16x16x64_i8 v[94:97], v[10:13], v[194:197], v[94:97]
	v_mfma_i32_16x16x64_i8 v[90:93], v[146:149], v[194:197], v[90:93]
	v_mfma_i32_16x16x64_i8 v[142:145], v[14:17], v[174:177], v[142:145]
	v_mfma_i32_16x16x64_i8 v[138:141], v[150:153], v[174:177], v[138:141]
	v_mfma_i32_16x16x64_i8 v[126:129], v[14:17], v[182:185], v[126:129]
	v_mfma_i32_16x16x64_i8 v[122:125], v[150:153], v[182:185], v[122:125]
	v_mfma_i32_16x16x64_i8 v[110:113], v[14:17], v[190:193], v[110:113]
	v_mfma_i32_16x16x64_i8 v[106:109], v[150:153], v[190:193], v[106:109]
	s_waitcnt lgkmcnt(0)
	v_mfma_i32_16x16x64_i8 v[94:97], v[14:17], v[198:201], v[94:97]
	v_mfma_i32_16x16x64_i8 v[90:93], v[150:153], v[198:201], v[90:93]
	s_setprio 0
	s_setprio 1
	v_mfma_i32_16x16x64_i8 v[134:137], v[154:157], v[170:173], v[134:137]
	v_mfma_i32_16x16x64_i8 v[130:133], v[162:165], v[170:173], v[130:133]
	v_mfma_i32_16x16x64_i8 v[118:121], v[154:157], v[178:181], v[118:121]
	v_mfma_i32_16x16x64_i8 v[114:117], v[162:165], v[178:181], v[114:117]
	v_mfma_i32_16x16x64_i8 v[102:105], v[154:157], v[186:189], v[102:105]
	v_mfma_i32_16x16x64_i8 v[98:101], v[162:165], v[186:189], v[98:101]
	v_mfma_i32_16x16x64_i8 v[86:89], v[154:157], v[194:197], v[86:89]
	v_mfma_i32_16x16x64_i8 v[82:85], v[162:165], v[194:197], v[82:85]
	v_mfma_i32_16x16x64_i8 v[134:137], v[158:161], v[174:177], v[134:137]
	v_mfma_i32_16x16x64_i8 v[130:133], v[166:169], v[174:177], v[130:133]
	v_mfma_i32_16x16x64_i8 v[118:121], v[158:161], v[182:185], v[118:121]
	v_mfma_i32_16x16x64_i8 v[114:117], v[166:169], v[182:185], v[114:117]
	v_mfma_i32_16x16x64_i8 v[102:105], v[158:161], v[190:193], v[102:105]
	v_mfma_i32_16x16x64_i8 v[98:101], v[166:169], v[190:193], v[98:101]
	v_mfma_i32_16x16x64_i8 v[86:89], v[158:161], v[198:201], v[86:89]
	v_mfma_i32_16x16x64_i8 v[82:85], v[166:169], v[198:201], v[82:85]
	s_setprio 0
	s_barrier
	ds_read_b128 v[170:173], v9 offset:16384
	ds_read_b128 v[174:177], v9 offset:17408
	s_mov_b32 m0, s29
	s_nop 0
	buffer_load_dwordx4 v6, s[8:11], s60 offen lds
	ds_read_b128 v[178:181], v9 offset:18432
	ds_read_b128 v[182:185], v9 offset:19456
	s_add_i32 s61, s60, 0x20000
	s_mov_b32 m0, s34
	s_nop 0
	buffer_load_dwordx4 v7, s[8:11], s60 offen lds
	ds_read_b128 v[186:189], v9 offset:20480
	ds_read_b128 v[190:193], v9 offset:21504
	s_nop 0
	s_mov_b32 m0, s35
	s_nop 0
	buffer_load_dwordx4 v6, s[8:11], s61 offen lds
	ds_read_b128 v[194:197], v9 offset:22528
	ds_read_b128 v[198:201], v9 offset:23552
	s_nop 0
	s_mov_b32 m0, s36
	s_nop 0
	buffer_load_dwordx4 v7, s[8:11], s61 offen lds
	s_nop 0
	s_mov_b32 m0, s28
	s_nop 0
	buffer_load_dwordx4 v6, s[12:15], s62 offen lds
	s_nop 0
	s_mov_b32 m0, s38
	s_nop 0
	buffer_load_dwordx4 v7, s[12:15], s62 offen lds
	s_waitcnt vmcnt(8)
	s_waitcnt lgkmcnt(0)
	s_barrier
	s_setprio 1
	s_waitcnt lgkmcnt(7)
	v_mfma_i32_16x16x64_i8 v[78:81], v[10:13], v[170:173], v[78:81]
	v_mfma_i32_16x16x64_i8 v[74:77], v[146:149], v[170:173], v[74:77]
	s_waitcnt lgkmcnt(5)
	v_mfma_i32_16x16x64_i8 v[62:65], v[10:13], v[178:181], v[62:65]
	v_mfma_i32_16x16x64_i8 v[58:61], v[146:149], v[178:181], v[58:61]
	s_waitcnt lgkmcnt(3)
	v_mfma_i32_16x16x64_i8 v[46:49], v[10:13], v[186:189], v[46:49]
	v_mfma_i32_16x16x64_i8 v[42:45], v[146:149], v[186:189], v[42:45]
	s_waitcnt lgkmcnt(1)
	v_mfma_i32_16x16x64_i8 v[10:13], v[10:13], v[194:197], v[30:33]
	v_mfma_i32_16x16x64_i8 v[78:81], v[14:17], v[174:177], v[78:81]
	v_mfma_i32_16x16x64_i8 v[74:77], v[150:153], v[174:177], v[74:77]
	v_mfma_i32_16x16x64_i8 v[62:65], v[14:17], v[182:185], v[62:65]
	v_mfma_i32_16x16x64_i8 v[58:61], v[150:153], v[182:185], v[58:61]
	v_mfma_i32_16x16x64_i8 v[46:49], v[14:17], v[190:193], v[46:49]
	v_mfma_i32_16x16x64_i8 v[42:45], v[150:153], v[190:193], v[42:45]
	s_waitcnt lgkmcnt(0)
	v_mfma_i32_16x16x64_i8 v[10:13], v[14:17], v[198:201], v[10:13]
	v_mfma_i32_16x16x64_i8 v[14:17], v[146:149], v[194:197], v[26:29]
	v_mfma_i32_16x16x64_i8 v[14:17], v[150:153], v[198:201], v[14:17]
	s_setprio 0
	s_setprio 1
	v_mfma_i32_16x16x64_i8 v[26:29], v[154:157], v[170:173], v[70:73]
	v_mfma_i32_16x16x64_i8 v[70:73], v[158:161], v[174:177], v[26:29]
	v_mfma_i32_16x16x64_i8 v[26:29], v[162:165], v[170:173], v[66:69]
	v_mfma_i32_16x16x64_i8 v[66:69], v[166:169], v[174:177], v[26:29]
	v_mfma_i32_16x16x64_i8 v[26:29], v[154:157], v[178:181], v[54:57]
	v_mfma_i32_16x16x64_i8 v[54:57], v[158:161], v[182:185], v[26:29]
	v_mfma_i32_16x16x64_i8 v[26:29], v[162:165], v[178:181], v[50:53]
	v_mfma_i32_16x16x64_i8 v[50:53], v[166:169], v[182:185], v[26:29]
	v_mfma_i32_16x16x64_i8 v[26:29], v[154:157], v[186:189], v[38:41]
	v_mfma_i32_16x16x64_i8 v[38:41], v[158:161], v[190:193], v[26:29]
	v_mfma_i32_16x16x64_i8 v[26:29], v[162:165], v[186:189], v[34:37]
	v_mfma_i32_16x16x64_i8 v[22:25], v[154:157], v[194:197], v[22:25]
	v_mfma_i32_16x16x64_i8 v[18:21], v[162:165], v[194:197], v[18:21]
	v_mfma_i32_16x16x64_i8 v[34:37], v[166:169], v[190:193], v[26:29]
	v_mfma_i32_16x16x64_i8 v[22:25], v[158:161], v[198:201], v[22:25]
	v_mfma_i32_16x16x64_i8 v[18:21], v[166:169], v[198:201], v[18:21]
	s_setprio 0
	s_barrier
	v_add_u32_e32 v150, 0x18000, v8
	v_add_u32_e32 v166, 0x1c000, v8
	ds_read_b128 v[26:29], v150
	ds_read_b128 v[30:33], v150 offset:1024
	ds_read_b128 v[146:149], v150 offset:2048
	ds_read_b128 v[150:153], v150 offset:3072
	ds_read_b128 v[154:157], v166
	ds_read_b128 v[158:161], v166 offset:1024
	ds_read_b128 v[162:165], v166 offset:2048
	ds_read_b128 v[166:169], v166 offset:3072
	s_add_i32 s61, s62, 0x20000
	s_mov_b32 m0, s40
	s_nop 0
	buffer_load_dwordx4 v6, s[12:15], s61 offen lds
	s_nop 0
	s_mov_b32 m0, s41
	s_nop 0
	buffer_load_dwordx4 v7, s[12:15], s61 offen lds
	ds_read_b128 v[170:173], v9 offset:32768
	ds_read_b128 v[174:177], v9 offset:33792
	ds_read_b128 v[178:181], v9 offset:34816
	ds_read_b128 v[182:185], v9 offset:35840
	ds_read_b128 v[186:189], v9 offset:36864
	ds_read_b128 v[190:193], v9 offset:37888
	ds_read_b128 v[194:197], v9 offset:38912
	ds_read_b128 v[198:201], v9 offset:39936
	s_waitcnt vmcnt(8)
	s_waitcnt lgkmcnt(0)
	s_barrier
	s_setprio 1
	s_waitcnt lgkmcnt(7)
	v_mfma_i32_16x16x64_i8 v[142:145], v[26:29], v[170:173], v[142:145]
	v_mfma_i32_16x16x64_i8 v[138:141], v[146:149], v[170:173], v[138:141]
	s_waitcnt lgkmcnt(5)
	v_mfma_i32_16x16x64_i8 v[126:129], v[26:29], v[178:181], v[126:129]
	v_mfma_i32_16x16x64_i8 v[122:125], v[146:149], v[178:181], v[122:125]
	s_waitcnt lgkmcnt(3)
	v_mfma_i32_16x16x64_i8 v[110:113], v[26:29], v[186:189], v[110:113]
	v_mfma_i32_16x16x64_i8 v[106:109], v[146:149], v[186:189], v[106:109]
	s_waitcnt lgkmcnt(1)
	v_mfma_i32_16x16x64_i8 v[94:97], v[26:29], v[194:197], v[94:97]
	v_mfma_i32_16x16x64_i8 v[90:93], v[146:149], v[194:197], v[90:93]
	v_mfma_i32_16x16x64_i8 v[142:145], v[30:33], v[174:177], v[142:145]
	v_mfma_i32_16x16x64_i8 v[138:141], v[150:153], v[174:177], v[138:141]
	v_mfma_i32_16x16x64_i8 v[126:129], v[30:33], v[182:185], v[126:129]
	v_mfma_i32_16x16x64_i8 v[122:125], v[150:153], v[182:185], v[122:125]
	v_mfma_i32_16x16x64_i8 v[110:113], v[30:33], v[190:193], v[110:113]
	v_mfma_i32_16x16x64_i8 v[106:109], v[150:153], v[190:193], v[106:109]
	s_waitcnt lgkmcnt(0)
	v_mfma_i32_16x16x64_i8 v[94:97], v[30:33], v[198:201], v[94:97]
	v_mfma_i32_16x16x64_i8 v[90:93], v[150:153], v[198:201], v[90:93]
	s_setprio 0
	s_setprio 1
	v_mfma_i32_16x16x64_i8 v[134:137], v[154:157], v[170:173], v[134:137]
	v_mfma_i32_16x16x64_i8 v[130:133], v[162:165], v[170:173], v[130:133]
	v_mfma_i32_16x16x64_i8 v[118:121], v[154:157], v[178:181], v[118:121]
	v_mfma_i32_16x16x64_i8 v[114:117], v[162:165], v[178:181], v[114:117]
	v_mfma_i32_16x16x64_i8 v[102:105], v[154:157], v[186:189], v[102:105]
	v_mfma_i32_16x16x64_i8 v[98:101], v[162:165], v[186:189], v[98:101]
	v_mfma_i32_16x16x64_i8 v[86:89], v[154:157], v[194:197], v[86:89]
	v_mfma_i32_16x16x64_i8 v[82:85], v[162:165], v[194:197], v[82:85]
	v_mfma_i32_16x16x64_i8 v[134:137], v[158:161], v[174:177], v[134:137]
	v_mfma_i32_16x16x64_i8 v[130:133], v[166:169], v[174:177], v[130:133]
	v_mfma_i32_16x16x64_i8 v[118:121], v[158:161], v[182:185], v[118:121]
	v_mfma_i32_16x16x64_i8 v[114:117], v[166:169], v[182:185], v[114:117]
	v_mfma_i32_16x16x64_i8 v[102:105], v[158:161], v[190:193], v[102:105]
	v_mfma_i32_16x16x64_i8 v[98:101], v[166:169], v[190:193], v[98:101]
	v_mfma_i32_16x16x64_i8 v[86:89], v[158:161], v[198:201], v[86:89]
	v_mfma_i32_16x16x64_i8 v[82:85], v[166:169], v[198:201], v[82:85]
	s_setprio 0
	s_barrier
	ds_read_b128 v[170:173], v9 offset:49152
	ds_read_b128 v[174:177], v9 offset:50176
	s_or_b32 s61, s60, 0x80
	s_mov_b32 m0, s42
	s_nop 0
	buffer_load_dwordx4 v6, s[8:11], s61 offen lds
	ds_read_b128 v[178:181], v9 offset:51200
	ds_read_b128 v[182:185], v9 offset:52224
	s_add_i32 s60, s60, 0x20080
	s_mov_b32 m0, s43
	s_nop 0
	buffer_load_dwordx4 v7, s[8:11], s61 offen lds
	ds_read_b128 v[186:189], v9 offset:53248
	ds_read_b128 v[190:193], v9 offset:54272
	s_nop 0
	s_mov_b32 m0, s46
	s_nop 0
	buffer_load_dwordx4 v6, s[8:11], s60 offen lds
	ds_read_b128 v[194:197], v9 offset:55296
	ds_read_b128 v[198:201], v9 offset:56320
	s_nop 0
	s_mov_b32 m0, s47
	s_nop 0
	buffer_load_dwordx4 v7, s[8:11], s60 offen lds
	s_nop 0
	s_mov_b32 m0, s44
	s_nop 0
	buffer_load_dwordx4 v6, s[12:15], s59 offen lds
	s_nop 0
	s_mov_b32 m0, s45
	s_nop 0
	buffer_load_dwordx4 v7, s[12:15], s59 offen lds
	s_waitcnt vmcnt(8)
	s_waitcnt lgkmcnt(0)
	s_barrier
	s_setprio 1
	s_waitcnt lgkmcnt(7)
	v_mfma_i32_16x16x64_i8 v[78:81], v[26:29], v[170:173], v[78:81]
	s_waitcnt lgkmcnt(5)
	v_mfma_i32_16x16x64_i8 v[62:65], v[26:29], v[178:181], v[62:65]
	s_waitcnt lgkmcnt(3)
	v_mfma_i32_16x16x64_i8 v[46:49], v[26:29], v[186:189], v[46:49]
	s_waitcnt lgkmcnt(1)
	v_mfma_i32_16x16x64_i8 v[10:13], v[26:29], v[194:197], v[10:13]
	v_mfma_i32_16x16x64_i8 v[78:81], v[30:33], v[174:177], v[78:81]
	v_mfma_i32_16x16x64_i8 v[74:77], v[146:149], v[170:173], v[74:77]
	v_mfma_i32_16x16x64_i8 v[62:65], v[30:33], v[182:185], v[62:65]
	v_mfma_i32_16x16x64_i8 v[58:61], v[146:149], v[178:181], v[58:61]
	v_mfma_i32_16x16x64_i8 v[46:49], v[30:33], v[190:193], v[46:49]
	v_mfma_i32_16x16x64_i8 v[42:45], v[146:149], v[186:189], v[42:45]
	s_waitcnt lgkmcnt(0)
	v_mfma_i32_16x16x64_i8 v[30:33], v[30:33], v[198:201], v[10:13]
	v_mfma_i32_16x16x64_i8 v[10:13], v[146:149], v[194:197], v[14:17]
	v_mfma_i32_16x16x64_i8 v[74:77], v[150:153], v[174:177], v[74:77]
	v_mfma_i32_16x16x64_i8 v[58:61], v[150:153], v[182:185], v[58:61]
	v_mfma_i32_16x16x64_i8 v[42:45], v[150:153], v[190:193], v[42:45]
	v_mfma_i32_16x16x64_i8 v[26:29], v[150:153], v[198:201], v[10:13]
	s_setprio 0
	s_setprio 1
	v_mfma_i32_16x16x64_i8 v[10:13], v[154:157], v[170:173], v[70:73]
	v_mfma_i32_16x16x64_i8 v[70:73], v[158:161], v[174:177], v[10:13]
	v_mfma_i32_16x16x64_i8 v[10:13], v[162:165], v[170:173], v[66:69]
	v_mfma_i32_16x16x64_i8 v[66:69], v[166:169], v[174:177], v[10:13]
	v_mfma_i32_16x16x64_i8 v[10:13], v[154:157], v[178:181], v[54:57]
	v_mfma_i32_16x16x64_i8 v[54:57], v[158:161], v[182:185], v[10:13]
	v_mfma_i32_16x16x64_i8 v[10:13], v[162:165], v[178:181], v[50:53]
	v_mfma_i32_16x16x64_i8 v[50:53], v[166:169], v[182:185], v[10:13]
	v_mfma_i32_16x16x64_i8 v[10:13], v[154:157], v[186:189], v[38:41]
	v_mfma_i32_16x16x64_i8 v[38:41], v[158:161], v[190:193], v[10:13]
	v_mfma_i32_16x16x64_i8 v[10:13], v[162:165], v[186:189], v[34:37]
	v_mfma_i32_16x16x64_i8 v[34:37], v[166:169], v[190:193], v[10:13]
	v_mfma_i32_16x16x64_i8 v[10:13], v[154:157], v[194:197], v[22:25]
	v_mfma_i32_16x16x64_i8 v[22:25], v[158:161], v[198:201], v[10:13]
	v_mfma_i32_16x16x64_i8 v[10:13], v[162:165], v[194:197], v[18:21]
	v_mfma_i32_16x16x64_i8 v[18:21], v[166:169], v[198:201], v[10:13]
	s_setprio 0
	s_add_i32 s55, s55, 2
	s_addk_i32 s58, 0x100
	s_cmp_lt_u32 s55, 6
	s_barrier
	s_cbranch_scc1 .LBB0_943
	s_andn2_b64 vcc, exec, s[6:7]
	s_cbranch_vccz .LBB0_935
	v_cvt_f32_i32_e32 v142, v142
	v_cvt_f32_i32_e32 v143, v143
	v_cvt_f32_i32_e32 v144, v144
	v_cvt_f32_i32_e32 v145, v145
	v_cvt_f32_i32_e32 v138, v138
	v_cvt_f32_i32_e32 v139, v139
	v_cvt_f32_i32_e32 v140, v140
	v_cvt_f32_i32_e32 v141, v141
	v_cvt_f32_i32_e32 v126, v126
	v_cvt_f32_i32_e32 v127, v127
	v_cvt_f32_i32_e32 v128, v128
	v_cvt_f32_i32_e32 v129, v129
	v_cvt_f32_i32_e32 v122, v122
	v_cvt_f32_i32_e32 v123, v123
	v_cvt_f32_i32_e32 v124, v124
	v_cvt_f32_i32_e32 v125, v125
	v_cvt_f32_i32_e32 v110, v110
	v_cvt_f32_i32_e32 v111, v111
	v_cvt_f32_i32_e32 v112, v112
	v_cvt_f32_i32_e32 v113, v113
	v_cvt_f32_i32_e32 v106, v106
	v_cvt_f32_i32_e32 v107, v107
	v_cvt_f32_i32_e32 v108, v108
	v_cvt_f32_i32_e32 v109, v109
	v_cvt_f32_i32_e32 v94, v94
	v_cvt_f32_i32_e32 v95, v95
	v_cvt_f32_i32_e32 v96, v96
	v_cvt_f32_i32_e32 v97, v97
	v_cvt_f32_i32_e32 v90, v90
	v_cvt_f32_i32_e32 v91, v91
	v_cvt_f32_i32_e32 v92, v92
	v_cvt_f32_i32_e32 v93, v93
	v_cvt_f32_i32_e32 v134, v134
	v_cvt_f32_i32_e32 v135, v135
	v_cvt_f32_i32_e32 v136, v136
	v_cvt_f32_i32_e32 v137, v137
	v_cvt_f32_i32_e32 v130, v130
	v_cvt_f32_i32_e32 v131, v131
	v_cvt_f32_i32_e32 v132, v132
	v_cvt_f32_i32_e32 v133, v133
	v_cvt_f32_i32_e32 v118, v118
	v_cvt_f32_i32_e32 v119, v119
	v_cvt_f32_i32_e32 v120, v120
	v_cvt_f32_i32_e32 v121, v121
	v_cvt_f32_i32_e32 v114, v114
	v_cvt_f32_i32_e32 v115, v115
	v_cvt_f32_i32_e32 v116, v116
	v_cvt_f32_i32_e32 v117, v117
	v_cvt_f32_i32_e32 v102, v102
	v_cvt_f32_i32_e32 v103, v103
	v_cvt_f32_i32_e32 v104, v104
	v_cvt_f32_i32_e32 v105, v105
	v_cvt_f32_i32_e32 v98, v98
	v_cvt_f32_i32_e32 v99, v99
	v_cvt_f32_i32_e32 v100, v100
	v_cvt_f32_i32_e32 v101, v101
	v_cvt_f32_i32_e32 v86, v86
	v_cvt_f32_i32_e32 v87, v87
	v_cvt_f32_i32_e32 v88, v88
	v_cvt_f32_i32_e32 v89, v89
	v_cvt_f32_i32_e32 v82, v82
	v_cvt_f32_i32_e32 v83, v83
	v_cvt_f32_i32_e32 v84, v84
	v_cvt_f32_i32_e32 v85, v85
	v_cvt_f32_i32_e32 v78, v78
	v_cvt_f32_i32_e32 v79, v79
	v_cvt_f32_i32_e32 v80, v80
	v_cvt_f32_i32_e32 v81, v81
	v_cvt_f32_i32_e32 v74, v74
	v_cvt_f32_i32_e32 v75, v75
	v_cvt_f32_i32_e32 v76, v76
	v_cvt_f32_i32_e32 v77, v77
	v_cvt_f32_i32_e32 v62, v62
	v_cvt_f32_i32_e32 v63, v63
	v_cvt_f32_i32_e32 v64, v64
	v_cvt_f32_i32_e32 v65, v65
	v_cvt_f32_i32_e32 v58, v58
	v_cvt_f32_i32_e32 v59, v59
	v_cvt_f32_i32_e32 v60, v60
	v_cvt_f32_i32_e32 v61, v61
	v_cvt_f32_i32_e32 v46, v46
	v_cvt_f32_i32_e32 v47, v47
	v_cvt_f32_i32_e32 v48, v48
	v_cvt_f32_i32_e32 v49, v49
	v_cvt_f32_i32_e32 v42, v42
	v_cvt_f32_i32_e32 v43, v43
	v_cvt_f32_i32_e32 v44, v44
	v_cvt_f32_i32_e32 v45, v45
	v_cvt_f32_i32_e32 v30, v30
	v_cvt_f32_i32_e32 v31, v31
	v_cvt_f32_i32_e32 v32, v32
	v_cvt_f32_i32_e32 v33, v33
	v_cvt_f32_i32_e32 v26, v26
	v_cvt_f32_i32_e32 v27, v27
	v_cvt_f32_i32_e32 v28, v28
	v_cvt_f32_i32_e32 v29, v29
	v_cvt_f32_i32_e32 v70, v70
	v_cvt_f32_i32_e32 v71, v71
	v_cvt_f32_i32_e32 v72, v72
	v_cvt_f32_i32_e32 v73, v73
	v_cvt_f32_i32_e32 v66, v66
	v_cvt_f32_i32_e32 v67, v67
	v_cvt_f32_i32_e32 v68, v68
	v_cvt_f32_i32_e32 v69, v69
	v_cvt_f32_i32_e32 v54, v54
	v_cvt_f32_i32_e32 v55, v55
	v_cvt_f32_i32_e32 v56, v56
	v_cvt_f32_i32_e32 v57, v57
	v_cvt_f32_i32_e32 v50, v50
	v_cvt_f32_i32_e32 v51, v51
	v_cvt_f32_i32_e32 v52, v52
	v_cvt_f32_i32_e32 v53, v53
	v_cvt_f32_i32_e32 v38, v38
	v_cvt_f32_i32_e32 v39, v39
	v_cvt_f32_i32_e32 v40, v40
	v_cvt_f32_i32_e32 v41, v41
	v_cvt_f32_i32_e32 v34, v34
	v_cvt_f32_i32_e32 v35, v35
	v_cvt_f32_i32_e32 v36, v36
	v_cvt_f32_i32_e32 v37, v37
	v_cvt_f32_i32_e32 v22, v22
	v_cvt_f32_i32_e32 v23, v23
	v_cvt_f32_i32_e32 v24, v24
	v_cvt_f32_i32_e32 v25, v25
	v_cvt_f32_i32_e32 v18, v18
	v_cvt_f32_i32_e32 v19, v19
	v_cvt_f32_i32_e32 v20, v20
	v_cvt_f32_i32_e32 v21, v21
	s_andn2_b64 vcc, exec, s[4:5]
	s_cbranch_vccnz .LBB0_936

.LBB0_1072:
	ds_read_b128 v[136:139], v152
	ds_read_b128 v[140:143], v152 offset:1024
	ds_read_b128 v[158:161], v152 offset:2048
	ds_read_b128 v[162:165], v152 offset:3072
	ds_read_b128 v[166:169], v153
	ds_read_b128 v[170:173], v153 offset:1024
	ds_read_b128 v[174:177], v153 offset:2048
	ds_read_b128 v[178:181], v153 offset:3072
	s_add_i32 s60, s55, 0xfffe0080
	s_cmp_eq_u32 s59, 4
	s_cselect_b32 s62, s1, s60
	s_cselect_b32 s61, s54, s58
	s_or_b32 s60, s62, 0x80
	s_mov_b32 m0, s42
	s_nop 0
	buffer_load_dwordx4 v146, s[12:15], s55 offen lds
	s_nop 0
	s_mov_b32 m0, s43
	s_nop 0
	buffer_load_dwordx4 v147, s[12:15], s55 offen lds
	ds_read_b128 v[182:185], v154
	ds_read_b128 v[186:189], v154 offset:1024
	ds_read_b128 v[190:193], v154 offset:2048
	ds_read_b128 v[194:197], v154 offset:3072
	ds_read_b128 v[198:201], v154 offset:4096
	ds_read_b128 v[202:205], v154 offset:5120
	ds_read_b128 v[206:209], v154 offset:6144
	ds_read_b128 v[210:213], v154 offset:7168
	s_waitcnt vmcnt(8)
	s_waitcnt lgkmcnt(0)
	s_barrier
	s_setprio 1
	s_waitcnt lgkmcnt(0)
	v_mfma_i32_16x16x64_i8 v[126:129], v[136:139], v[182:185], v[126:129]
	v_mfma_i32_16x16x64_i8 v[122:125], v[158:161], v[182:185], v[122:125]
	v_mfma_i32_16x16x64_i8 v[118:121], v[136:139], v[190:193], v[118:121]
	v_mfma_i32_16x16x64_i8 v[114:117], v[158:161], v[190:193], v[114:117]
	v_mfma_i32_16x16x64_i8 v[110:113], v[136:139], v[198:201], v[110:113]
	v_mfma_i32_16x16x64_i8 v[106:109], v[158:161], v[198:201], v[106:109]
	v_mfma_i32_16x16x64_i8 v[102:105], v[136:139], v[206:209], v[102:105]
	v_mfma_i32_16x16x64_i8 v[98:101], v[158:161], v[206:209], v[98:101]
	v_mfma_i32_16x16x64_i8 v[126:129], v[140:143], v[186:189], v[126:129]
	v_mfma_i32_16x16x64_i8 v[122:125], v[162:165], v[186:189], v[122:125]
	v_mfma_i32_16x16x64_i8 v[118:121], v[140:143], v[194:197], v[118:121]
	v_mfma_i32_16x16x64_i8 v[114:117], v[162:165], v[194:197], v[114:117]
	v_mfma_i32_16x16x64_i8 v[110:113], v[140:143], v[202:205], v[110:113]
	v_mfma_i32_16x16x64_i8 v[106:109], v[162:165], v[202:205], v[106:109]
	v_mfma_i32_16x16x64_i8 v[102:105], v[140:143], v[210:213], v[102:105]
	v_mfma_i32_16x16x64_i8 v[98:101], v[162:165], v[210:213], v[98:101]
	s_setprio 0
	s_setprio 1
	v_mfma_i32_16x16x64_i8 v[94:97], v[166:169], v[182:185], v[94:97]
	v_mfma_i32_16x16x64_i8 v[90:93], v[174:177], v[182:185], v[90:93]
	v_mfma_i32_16x16x64_i8 v[86:89], v[166:169], v[190:193], v[86:89]
	v_mfma_i32_16x16x64_i8 v[82:85], v[174:177], v[190:193], v[82:85]
	v_mfma_i32_16x16x64_i8 v[78:81], v[166:169], v[198:201], v[78:81]
	v_mfma_i32_16x16x64_i8 v[74:77], v[174:177], v[198:201], v[74:77]
	v_mfma_i32_16x16x64_i8 v[70:73], v[166:169], v[206:209], v[70:73]
	v_mfma_i32_16x16x64_i8 v[66:69], v[174:177], v[206:209], v[66:69]
	v_mfma_i32_16x16x64_i8 v[94:97], v[170:173], v[186:189], v[94:97]
	v_mfma_i32_16x16x64_i8 v[90:93], v[178:181], v[186:189], v[90:93]
	v_mfma_i32_16x16x64_i8 v[86:89], v[170:173], v[194:197], v[86:89]
	v_mfma_i32_16x16x64_i8 v[82:85], v[178:181], v[194:197], v[82:85]
	v_mfma_i32_16x16x64_i8 v[78:81], v[170:173], v[202:205], v[78:81]
	v_mfma_i32_16x16x64_i8 v[74:77], v[178:181], v[202:205], v[74:77]
	v_mfma_i32_16x16x64_i8 v[70:73], v[170:173], v[210:213], v[70:73]
	v_mfma_i32_16x16x64_i8 v[66:69], v[178:181], v[210:213], v[66:69]
	s_setprio 0
	s_barrier
	ds_read_b128 v[182:185], v154 offset:16384
	ds_read_b128 v[186:189], v154 offset:17408
	s_mov_b32 m0, s27
	s_nop 0
	buffer_load_dwordx4 v144, s[8:11], s61 offen lds
	ds_read_b128 v[190:193], v154 offset:18432
	ds_read_b128 v[194:197], v154 offset:19456
	s_add_i32 s63, s61, 0x20000
	s_mov_b32 m0, s28
	s_nop 0
	buffer_load_dwordx4 v145, s[8:11], s61 offen lds
	ds_read_b128 v[198:201], v154 offset:20480
	ds_read_b128 v[202:205], v154 offset:21504
	s_nop 0
	s_mov_b32 m0, s29
	s_nop 0
	buffer_load_dwordx4 v144, s[8:11], s63 offen lds
	ds_read_b128 v[206:209], v154 offset:22528
	ds_read_b128 v[210:213], v154 offset:23552
	s_nop 0
	s_mov_b32 m0, s30
	s_nop 0
	buffer_load_dwordx4 v145, s[8:11], s63 offen lds
	s_nop 0
	s_mov_b32 m0, s26
	s_nop 0
	buffer_load_dwordx4 v146, s[12:15], s62 offen lds
	s_nop 0
	s_mov_b32 m0, s2
	s_nop 0
	buffer_load_dwordx4 v147, s[12:15], s62 offen lds
	s_waitcnt vmcnt(8)
	s_waitcnt lgkmcnt(0)
	s_barrier
	s_setprio 1
	s_waitcnt lgkmcnt(0)
	v_mfma_i32_16x16x64_i8 v[62:65], v[136:139], v[182:185], v[62:65]
	v_mfma_i32_16x16x64_i8 v[58:61], v[158:161], v[182:185], v[58:61]
	v_mfma_i32_16x16x64_i8 v[54:57], v[136:139], v[190:193], v[54:57]
	v_mfma_i32_16x16x64_i8 v[50:53], v[158:161], v[190:193], v[50:53]
	v_mfma_i32_16x16x64_i8 v[46:49], v[136:139], v[198:201], v[46:49]
	v_mfma_i32_16x16x64_i8 v[42:45], v[158:161], v[198:201], v[42:45]
	v_mfma_i32_16x16x64_i8 v[38:41], v[136:139], v[206:209], v[38:41]
	v_mfma_i32_16x16x64_i8 v[34:37], v[158:161], v[206:209], v[34:37]
	v_mfma_i32_16x16x64_i8 v[62:65], v[140:143], v[186:189], v[62:65]
	v_mfma_i32_16x16x64_i8 v[58:61], v[162:165], v[186:189], v[58:61]
	v_mfma_i32_16x16x64_i8 v[54:57], v[140:143], v[194:197], v[54:57]
	v_mfma_i32_16x16x64_i8 v[50:53], v[162:165], v[194:197], v[50:53]
	v_mfma_i32_16x16x64_i8 v[46:49], v[140:143], v[202:205], v[46:49]
	v_mfma_i32_16x16x64_i8 v[42:45], v[162:165], v[202:205], v[42:45]
	v_mfma_i32_16x16x64_i8 v[38:41], v[140:143], v[210:213], v[38:41]
	v_mfma_i32_16x16x64_i8 v[34:37], v[162:165], v[210:213], v[34:37]
	s_setprio 0
	s_setprio 1
	v_mfma_i32_16x16x64_i8 v[30:33], v[166:169], v[182:185], v[30:33]
	v_mfma_i32_16x16x64_i8 v[26:29], v[174:177], v[182:185], v[26:29]
	v_mfma_i32_16x16x64_i8 v[22:25], v[166:169], v[190:193], v[22:25]
	v_mfma_i32_16x16x64_i8 v[18:21], v[174:177], v[190:193], v[18:21]
	v_mfma_i32_16x16x64_i8 v[14:17], v[166:169], v[198:201], v[14:17]
	v_mfma_i32_16x16x64_i8 v[10:13], v[174:177], v[198:201], v[10:13]
	v_mfma_i32_16x16x64_i8 v[6:9], v[166:169], v[206:209], v[6:9]
	v_mfma_i32_16x16x64_i8 v[2:5], v[174:177], v[206:209], v[2:5]
	v_mfma_i32_16x16x64_i8 v[30:33], v[170:173], v[186:189], v[30:33]
	v_mfma_i32_16x16x64_i8 v[26:29], v[178:181], v[186:189], v[26:29]
	v_mfma_i32_16x16x64_i8 v[22:25], v[170:173], v[194:197], v[22:25]
	v_mfma_i32_16x16x64_i8 v[18:21], v[178:181], v[194:197], v[18:21]
	v_mfma_i32_16x16x64_i8 v[14:17], v[170:173], v[202:205], v[14:17]
	v_mfma_i32_16x16x64_i8 v[10:13], v[178:181], v[202:205], v[10:13]
	v_mfma_i32_16x16x64_i8 v[6:9], v[170:173], v[210:213], v[6:9]
	v_mfma_i32_16x16x64_i8 v[2:5], v[178:181], v[210:213], v[2:5]
	s_setprio 0
	s_barrier
	ds_read_b128 v[136:139], v155
	ds_read_b128 v[140:143], v155 offset:1024
	ds_read_b128 v[158:161], v155 offset:2048
	ds_read_b128 v[162:165], v155 offset:3072
	ds_read_b128 v[166:169], v156
	ds_read_b128 v[170:173], v156 offset:1024
	ds_read_b128 v[174:177], v156 offset:2048
	ds_read_b128 v[178:181], v156 offset:3072
	s_add_i32 s62, s62, 0x20000
	s_mov_b32 m0, s3
	s_nop 0
	buffer_load_dwordx4 v146, s[12:15], s62 offen lds
	s_nop 0
	s_mov_b32 m0, s31
	s_nop 0
	buffer_load_dwordx4 v147, s[12:15], s62 offen lds
	ds_read_b128 v[182:185], v154 offset:32768
	ds_read_b128 v[186:189], v154 offset:33792
	ds_read_b128 v[190:193], v154 offset:34816
	ds_read_b128 v[194:197], v154 offset:35840
	ds_read_b128 v[198:201], v154 offset:36864
	ds_read_b128 v[202:205], v154 offset:37888
	ds_read_b128 v[206:209], v154 offset:38912
	ds_read_b128 v[210:213], v154 offset:39936
	s_waitcnt vmcnt(8)
	s_waitcnt lgkmcnt(0)
	s_barrier
	s_setprio 1
	s_waitcnt lgkmcnt(0)
	v_mfma_i32_16x16x64_i8 v[126:129], v[136:139], v[182:185], v[126:129]
	v_mfma_i32_16x16x64_i8 v[122:125], v[158:161], v[182:185], v[122:125]
	v_mfma_i32_16x16x64_i8 v[118:121], v[136:139], v[190:193], v[118:121]
	v_mfma_i32_16x16x64_i8 v[114:117], v[158:161], v[190:193], v[114:117]
	v_mfma_i32_16x16x64_i8 v[110:113], v[136:139], v[198:201], v[110:113]
	v_mfma_i32_16x16x64_i8 v[106:109], v[158:161], v[198:201], v[106:109]
	v_mfma_i32_16x16x64_i8 v[102:105], v[136:139], v[206:209], v[102:105]
	v_mfma_i32_16x16x64_i8 v[98:101], v[158:161], v[206:209], v[98:101]
	v_mfma_i32_16x16x64_i8 v[126:129], v[140:143], v[186:189], v[126:129]
	v_mfma_i32_16x16x64_i8 v[122:125], v[162:165], v[186:189], v[122:125]
	v_mfma_i32_16x16x64_i8 v[118:121], v[140:143], v[194:197], v[118:121]
	v_mfma_i32_16x16x64_i8 v[114:117], v[162:165], v[194:197], v[114:117]
	v_mfma_i32_16x16x64_i8 v[110:113], v[140:143], v[202:205], v[110:113]
	v_mfma_i32_16x16x64_i8 v[106:109], v[162:165], v[202:205], v[106:109]
	v_mfma_i32_16x16x64_i8 v[102:105], v[140:143], v[210:213], v[102:105]
	v_mfma_i32_16x16x64_i8 v[98:101], v[162:165], v[210:213], v[98:101]
	s_setprio 0
	s_setprio 1
	v_mfma_i32_16x16x64_i8 v[94:97], v[166:169], v[182:185], v[94:97]
	v_mfma_i32_16x16x64_i8 v[90:93], v[174:177], v[182:185], v[90:93]
	v_mfma_i32_16x16x64_i8 v[86:89], v[166:169], v[190:193], v[86:89]
	v_mfma_i32_16x16x64_i8 v[82:85], v[174:177], v[190:193], v[82:85]
	v_mfma_i32_16x16x64_i8 v[78:81], v[166:169], v[198:201], v[78:81]
	v_mfma_i32_16x16x64_i8 v[74:77], v[174:177], v[198:201], v[74:77]
	v_mfma_i32_16x16x64_i8 v[70:73], v[166:169], v[206:209], v[70:73]
	v_mfma_i32_16x16x64_i8 v[66:69], v[174:177], v[206:209], v[66:69]
	v_mfma_i32_16x16x64_i8 v[94:97], v[170:173], v[186:189], v[94:97]
	v_mfma_i32_16x16x64_i8 v[90:93], v[178:181], v[186:189], v[90:93]
	v_mfma_i32_16x16x64_i8 v[86:89], v[170:173], v[194:197], v[86:89]
	v_mfma_i32_16x16x64_i8 v[82:85], v[178:181], v[194:197], v[82:85]
	v_mfma_i32_16x16x64_i8 v[78:81], v[170:173], v[202:205], v[78:81]
	v_mfma_i32_16x16x64_i8 v[74:77], v[178:181], v[202:205], v[74:77]
	v_mfma_i32_16x16x64_i8 v[70:73], v[170:173], v[210:213], v[70:73]
	v_mfma_i32_16x16x64_i8 v[66:69], v[178:181], v[210:213], v[66:69]
	s_setprio 0
	s_barrier
	ds_read_b128 v[182:185], v154 offset:49152
	ds_read_b128 v[186:189], v154 offset:50176
	s_or_b32 s62, s61, 0x80
	s_mov_b32 m0, s35
	s_nop 0
	buffer_load_dwordx4 v144, s[8:11], s62 offen lds
	ds_read_b128 v[190:193], v154 offset:51200
	ds_read_b128 v[194:197], v154 offset:52224
	s_add_i32 s61, s61, 0x20080
	s_mov_b32 m0, s36
	s_nop 0
	buffer_load_dwordx4 v145, s[8:11], s62 offen lds
	ds_read_b128 v[198:201], v154 offset:53248
	ds_read_b128 v[202:205], v154 offset:54272
	s_nop 0
	s_mov_b32 m0, s39
	s_nop 0
	buffer_load_dwordx4 v144, s[8:11], s61 offen lds
	ds_read_b128 v[206:209], v154 offset:55296
	ds_read_b128 v[210:213], v154 offset:56320
	s_nop 0
	s_mov_b32 m0, s40
	s_nop 0
	buffer_load_dwordx4 v145, s[8:11], s61 offen lds
	s_nop 0
	s_mov_b32 m0, s37
	s_nop 0
	buffer_load_dwordx4 v146, s[12:15], s60 offen lds
	s_nop 0
	s_mov_b32 m0, s38
	s_nop 0
	buffer_load_dwordx4 v147, s[12:15], s60 offen lds
	s_waitcnt vmcnt(8)
	s_waitcnt lgkmcnt(0)
	s_barrier
	s_setprio 1
	s_waitcnt lgkmcnt(0)
	v_mfma_i32_16x16x64_i8 v[62:65], v[136:139], v[182:185], v[62:65]
	v_mfma_i32_16x16x64_i8 v[58:61], v[158:161], v[182:185], v[58:61]
	v_mfma_i32_16x16x64_i8 v[54:57], v[136:139], v[190:193], v[54:57]
	v_mfma_i32_16x16x64_i8 v[50:53], v[158:161], v[190:193], v[50:53]
	v_mfma_i32_16x16x64_i8 v[46:49], v[136:139], v[198:201], v[46:49]
	v_mfma_i32_16x16x64_i8 v[42:45], v[158:161], v[198:201], v[42:45]
	v_mfma_i32_16x16x64_i8 v[38:41], v[136:139], v[206:209], v[38:41]
	v_mfma_i32_16x16x64_i8 v[34:37], v[158:161], v[206:209], v[34:37]
	v_mfma_i32_16x16x64_i8 v[62:65], v[140:143], v[186:189], v[62:65]
	v_mfma_i32_16x16x64_i8 v[58:61], v[162:165], v[186:189], v[58:61]
	v_mfma_i32_16x16x64_i8 v[54:57], v[140:143], v[194:197], v[54:57]
	v_mfma_i32_16x16x64_i8 v[50:53], v[162:165], v[194:197], v[50:53]
	v_mfma_i32_16x16x64_i8 v[46:49], v[140:143], v[202:205], v[46:49]
	v_mfma_i32_16x16x64_i8 v[42:45], v[162:165], v[202:205], v[42:45]
	v_mfma_i32_16x16x64_i8 v[38:41], v[140:143], v[210:213], v[38:41]
	v_mfma_i32_16x16x64_i8 v[34:37], v[162:165], v[210:213], v[34:37]
	s_setprio 0
	s_setprio 1
	v_mfma_i32_16x16x64_i8 v[30:33], v[166:169], v[182:185], v[30:33]
	v_mfma_i32_16x16x64_i8 v[26:29], v[174:177], v[182:185], v[26:29]
	v_mfma_i32_16x16x64_i8 v[22:25], v[166:169], v[190:193], v[22:25]
	v_mfma_i32_16x16x64_i8 v[18:21], v[174:177], v[190:193], v[18:21]
	v_mfma_i32_16x16x64_i8 v[14:17], v[166:169], v[198:201], v[14:17]
	v_mfma_i32_16x16x64_i8 v[10:13], v[174:177], v[198:201], v[10:13]
	v_mfma_i32_16x16x64_i8 v[6:9], v[166:169], v[206:209], v[6:9]
	v_mfma_i32_16x16x64_i8 v[2:5], v[174:177], v[206:209], v[2:5]
	v_mfma_i32_16x16x64_i8 v[30:33], v[170:173], v[186:189], v[30:33]
	v_mfma_i32_16x16x64_i8 v[26:29], v[178:181], v[186:189], v[26:29]
	v_mfma_i32_16x16x64_i8 v[22:25], v[170:173], v[194:197], v[22:25]
	v_mfma_i32_16x16x64_i8 v[18:21], v[178:181], v[194:197], v[18:21]
	v_mfma_i32_16x16x64_i8 v[14:17], v[170:173], v[202:205], v[14:17]
	v_mfma_i32_16x16x64_i8 v[10:13], v[178:181], v[202:205], v[10:13]
	v_mfma_i32_16x16x64_i8 v[6:9], v[170:173], v[210:213], v[6:9]
	v_mfma_i32_16x16x64_i8 v[2:5], v[178:181], v[210:213], v[2:5]
	s_setprio 0
	s_add_i32 s59, s59, 2
	s_addk_i32 s55, 0x100
	s_addk_i32 s58, 0x100
	s_cmp_gt_u32 s59, 5
	s_barrier
	s_cbranch_scc0 .LBB0_1072
	s_and_b64 vcc, exec, s[20:21]
	s_cbranch_vccz .LBB0_1075
	s_barrier

.LBB0_1135:
	v_add_u32_e32 v150, 0x10000, v136
	v_add_u32_e32 v166, 0x14000, v136
	ds_read_b128 v[138:141], v150
	ds_read_b128 v[142:145], v150 offset:1024
	ds_read_b128 v[146:149], v150 offset:2048
	ds_read_b128 v[150:153], v150 offset:3072
	ds_read_b128 v[154:157], v166
	ds_read_b128 v[158:161], v166 offset:1024
	ds_read_b128 v[162:165], v166 offset:2048
	ds_read_b128 v[166:169], v166 offset:3072
	s_add_i32 s57, s36, s3
	s_add_i32 s56, s30, s3
	s_add_i32 s55, s57, 0x1600
	s_addk_i32 s56, 0x1600
	s_cmp_eq_u32 s3, 0
	s_cselect_b32 s58, s53, s55
	s_cselect_b32 s56, s54, s56
	s_add_i32 s55, s58, 0x80
	s_add_i32 s57, s57, 0xb1580
	s_mov_b32 m0, s46
	s_nop 0
	buffer_load_dwordx4 v134, s[16:19], s57 offen lds
	s_nop 0
	s_mov_b32 m0, s47
	s_nop 0
	buffer_load_dwordx4 v135, s[16:19], s57 offen lds
	ds_read_b128 v[170:173], v137
	ds_read_b128 v[174:177], v137 offset:1024
	ds_read_b128 v[178:181], v137 offset:2048
	ds_read_b128 v[182:185], v137 offset:3072
	ds_read_b128 v[186:189], v137 offset:4096
	ds_read_b128 v[190:193], v137 offset:5120
	ds_read_b128 v[194:197], v137 offset:6144
	ds_read_b128 v[198:201], v137 offset:7168
	s_waitcnt vmcnt(8)
	s_waitcnt lgkmcnt(0)
	s_barrier
	s_setprio 1
	s_waitcnt lgkmcnt(7)
	v_mfma_f32_16x16x32_bf16 v[126:129], v[138:141], v[170:173], v[126:129]
	v_mfma_f32_16x16x32_bf16 v[122:125], v[146:149], v[170:173], v[122:125]
	s_waitcnt lgkmcnt(5)
	v_mfma_f32_16x16x32_bf16 v[118:121], v[138:141], v[178:181], v[118:121]
	v_mfma_f32_16x16x32_bf16 v[106:109], v[146:149], v[178:181], v[106:109]
	s_waitcnt lgkmcnt(3)
	v_mfma_f32_16x16x32_bf16 v[102:105], v[138:141], v[186:189], v[102:105]
	v_mfma_f32_16x16x32_bf16 v[90:93], v[146:149], v[186:189], v[90:93]
	s_waitcnt lgkmcnt(1)
	v_mfma_f32_16x16x32_bf16 v[86:89], v[138:141], v[194:197], v[86:89]
	v_mfma_f32_16x16x32_bf16 v[74:77], v[146:149], v[194:197], v[74:77]
	v_mfma_f32_16x16x32_bf16 v[126:129], v[142:145], v[174:177], v[126:129]
	v_mfma_f32_16x16x32_bf16 v[122:125], v[150:153], v[174:177], v[122:125]
	v_mfma_f32_16x16x32_bf16 v[118:121], v[142:145], v[182:185], v[118:121]
	v_mfma_f32_16x16x32_bf16 v[106:109], v[150:153], v[182:185], v[106:109]
	v_mfma_f32_16x16x32_bf16 v[102:105], v[142:145], v[190:193], v[102:105]
	v_mfma_f32_16x16x32_bf16 v[90:93], v[150:153], v[190:193], v[90:93]
	s_waitcnt lgkmcnt(0)
	v_mfma_f32_16x16x32_bf16 v[86:89], v[142:145], v[198:201], v[86:89]
	v_mfma_f32_16x16x32_bf16 v[74:77], v[150:153], v[198:201], v[74:77]
	s_setprio 0
	s_setprio 1
	v_mfma_f32_16x16x32_bf16 v[114:117], v[154:157], v[170:173], v[114:117]
	v_mfma_f32_16x16x32_bf16 v[110:113], v[162:165], v[170:173], v[110:113]
	v_mfma_f32_16x16x32_bf16 v[98:101], v[154:157], v[178:181], v[98:101]
	v_mfma_f32_16x16x32_bf16 v[94:97], v[162:165], v[178:181], v[94:97]
	v_mfma_f32_16x16x32_bf16 v[82:85], v[154:157], v[186:189], v[82:85]
	v_mfma_f32_16x16x32_bf16 v[78:81], v[162:165], v[186:189], v[78:81]
	v_mfma_f32_16x16x32_bf16 v[70:73], v[154:157], v[194:197], v[70:73]
	v_mfma_f32_16x16x32_bf16 v[66:69], v[162:165], v[194:197], v[66:69]
	v_mfma_f32_16x16x32_bf16 v[114:117], v[158:161], v[174:177], v[114:117]
	v_mfma_f32_16x16x32_bf16 v[110:113], v[166:169], v[174:177], v[110:113]
	v_mfma_f32_16x16x32_bf16 v[98:101], v[158:161], v[182:185], v[98:101]
	v_mfma_f32_16x16x32_bf16 v[94:97], v[166:169], v[182:185], v[94:97]
	v_mfma_f32_16x16x32_bf16 v[82:85], v[158:161], v[190:193], v[82:85]
	v_mfma_f32_16x16x32_bf16 v[78:81], v[166:169], v[190:193], v[78:81]
	v_mfma_f32_16x16x32_bf16 v[70:73], v[158:161], v[198:201], v[70:73]
	v_mfma_f32_16x16x32_bf16 v[66:69], v[166:169], v[198:201], v[66:69]
	s_setprio 0
	s_barrier
	ds_read_b128 v[170:173], v137 offset:16384
	ds_read_b128 v[174:177], v137 offset:17408
	s_mov_b32 m0, s29
	s_nop 0
	buffer_load_dwordx4 v134, s[12:15], s56 offen lds
	ds_read_b128 v[178:181], v137 offset:18432
	ds_read_b128 v[182:185], v137 offset:19456
	s_add_i32 s57, s56, 0xb0000
	s_mov_b32 m0, s33
	s_nop 0
	buffer_load_dwordx4 v135, s[12:15], s56 offen lds
	ds_read_b128 v[186:189], v137 offset:20480
	ds_read_b128 v[190:193], v137 offset:21504
	s_nop 0
	s_mov_b32 m0, s34
	s_nop 0
	buffer_load_dwordx4 v134, s[12:15], s57 offen lds
	ds_read_b128 v[194:197], v137 offset:22528
	ds_read_b128 v[198:201], v137 offset:23552
	s_nop 0
	s_mov_b32 m0, s35
	s_nop 0
	buffer_load_dwordx4 v135, s[12:15], s57 offen lds
	s_nop 0
	s_mov_b32 m0, s28
	s_nop 0
	buffer_load_dwordx4 v134, s[16:19], s58 offen lds
	s_nop 0
	s_mov_b32 m0, s37
	s_nop 0
	buffer_load_dwordx4 v135, s[16:19], s58 offen lds
	s_waitcnt vmcnt(8)
	s_waitcnt lgkmcnt(0)
	s_barrier
	s_setprio 1
	s_waitcnt lgkmcnt(7)
	v_mfma_f32_16x16x32_bf16 v[62:65], v[138:141], v[170:173], v[62:65]
	v_mfma_f32_16x16x32_bf16 v[58:61], v[146:149], v[170:173], v[58:61]
	s_waitcnt lgkmcnt(5)
	v_mfma_f32_16x16x32_bf16 v[54:57], v[138:141], v[178:181], v[54:57]
	v_mfma_f32_16x16x32_bf16 v[42:45], v[146:149], v[178:181], v[42:45]
	s_waitcnt lgkmcnt(3)
	v_mfma_f32_16x16x32_bf16 v[38:41], v[138:141], v[186:189], v[38:41]
	v_mfma_f32_16x16x32_bf16 v[26:29], v[146:149], v[186:189], v[26:29]
	s_waitcnt lgkmcnt(1)
	v_mfma_f32_16x16x32_bf16 v[18:21], v[138:141], v[194:197], v[18:21]
	v_mfma_f32_16x16x32_bf16 v[10:13], v[146:149], v[194:197], v[10:13]
	v_mfma_f32_16x16x32_bf16 v[62:65], v[142:145], v[174:177], v[62:65]
	v_mfma_f32_16x16x32_bf16 v[58:61], v[150:153], v[174:177], v[58:61]
	v_mfma_f32_16x16x32_bf16 v[54:57], v[142:145], v[182:185], v[54:57]
	v_mfma_f32_16x16x32_bf16 v[42:45], v[150:153], v[182:185], v[42:45]
	v_mfma_f32_16x16x32_bf16 v[38:41], v[142:145], v[190:193], v[38:41]
	v_mfma_f32_16x16x32_bf16 v[26:29], v[150:153], v[190:193], v[26:29]
	s_waitcnt lgkmcnt(0)
	v_mfma_f32_16x16x32_bf16 v[18:21], v[142:145], v[198:201], v[18:21]
	v_mfma_f32_16x16x32_bf16 v[10:13], v[150:153], v[198:201], v[10:13]
	s_setprio 0
	s_setprio 1
	v_mfma_f32_16x16x32_bf16 v[50:53], v[154:157], v[170:173], v[50:53]
	v_mfma_f32_16x16x32_bf16 v[46:49], v[162:165], v[170:173], v[46:49]
	v_mfma_f32_16x16x32_bf16 v[34:37], v[154:157], v[178:181], v[34:37]
	v_mfma_f32_16x16x32_bf16 v[30:33], v[162:165], v[178:181], v[30:33]
	v_mfma_f32_16x16x32_bf16 v[22:25], v[154:157], v[186:189], v[22:25]
	v_mfma_f32_16x16x32_bf16 v[14:17], v[162:165], v[186:189], v[14:17]
	v_mfma_f32_16x16x32_bf16 v[6:9], v[154:157], v[194:197], v[6:9]
	v_mfma_f32_16x16x32_bf16 v[2:5], v[162:165], v[194:197], v[2:5]
	v_mfma_f32_16x16x32_bf16 v[50:53], v[158:161], v[174:177], v[50:53]
	v_mfma_f32_16x16x32_bf16 v[46:49], v[166:169], v[174:177], v[46:49]
	v_mfma_f32_16x16x32_bf16 v[34:37], v[158:161], v[182:185], v[34:37]
	v_mfma_f32_16x16x32_bf16 v[30:33], v[166:169], v[182:185], v[30:33]
	v_mfma_f32_16x16x32_bf16 v[22:25], v[158:161], v[190:193], v[22:25]
	v_mfma_f32_16x16x32_bf16 v[14:17], v[166:169], v[190:193], v[14:17]
	v_mfma_f32_16x16x32_bf16 v[6:9], v[158:161], v[198:201], v[6:9]
	v_mfma_f32_16x16x32_bf16 v[2:5], v[166:169], v[198:201], v[2:5]
	s_setprio 0
	s_barrier
	v_add_u32_e32 v150, 0x18000, v136
	v_add_u32_e32 v166, 0x1c000, v136
	ds_read_b128 v[138:141], v150
	ds_read_b128 v[142:145], v150 offset:1024
	ds_read_b128 v[146:149], v150 offset:2048
	ds_read_b128 v[150:153], v150 offset:3072
	ds_read_b128 v[154:157], v166
	ds_read_b128 v[158:161], v166 offset:1024
	ds_read_b128 v[162:165], v166 offset:2048
	ds_read_b128 v[166:169], v166 offset:3072
	s_add_i32 s57, s58, 0xb0000
	s_mov_b32 m0, s38
	s_nop 0
	buffer_load_dwordx4 v134, s[16:19], s57 offen lds
	s_nop 0
	s_mov_b32 m0, s39
	s_nop 0
	buffer_load_dwordx4 v135, s[16:19], s57 offen lds
	ds_read_b128 v[170:173], v137 offset:32768
	ds_read_b128 v[174:177], v137 offset:33792
	ds_read_b128 v[178:181], v137 offset:34816
	ds_read_b128 v[182:185], v137 offset:35840
	ds_read_b128 v[186:189], v137 offset:36864
	ds_read_b128 v[190:193], v137 offset:37888
	ds_read_b128 v[194:197], v137 offset:38912
	ds_read_b128 v[198:201], v137 offset:39936
	s_waitcnt vmcnt(8)
	s_waitcnt lgkmcnt(0)
	s_barrier
	s_setprio 1
	s_waitcnt lgkmcnt(7)
	v_mfma_f32_16x16x32_bf16 v[126:129], v[138:141], v[170:173], v[126:129]
	v_mfma_f32_16x16x32_bf16 v[122:125], v[146:149], v[170:173], v[122:125]
	s_waitcnt lgkmcnt(5)
	v_mfma_f32_16x16x32_bf16 v[118:121], v[138:141], v[178:181], v[118:121]
	v_mfma_f32_16x16x32_bf16 v[106:109], v[146:149], v[178:181], v[106:109]
	s_waitcnt lgkmcnt(3)
	v_mfma_f32_16x16x32_bf16 v[102:105], v[138:141], v[186:189], v[102:105]
	v_mfma_f32_16x16x32_bf16 v[90:93], v[146:149], v[186:189], v[90:93]
	s_waitcnt lgkmcnt(1)
	v_mfma_f32_16x16x32_bf16 v[86:89], v[138:141], v[194:197], v[86:89]
	v_mfma_f32_16x16x32_bf16 v[74:77], v[146:149], v[194:197], v[74:77]
	v_mfma_f32_16x16x32_bf16 v[126:129], v[142:145], v[174:177], v[126:129]
	v_mfma_f32_16x16x32_bf16 v[122:125], v[150:153], v[174:177], v[122:125]
	v_mfma_f32_16x16x32_bf16 v[118:121], v[142:145], v[182:185], v[118:121]
	v_mfma_f32_16x16x32_bf16 v[106:109], v[150:153], v[182:185], v[106:109]
	v_mfma_f32_16x16x32_bf16 v[102:105], v[142:145], v[190:193], v[102:105]
	v_mfma_f32_16x16x32_bf16 v[90:93], v[150:153], v[190:193], v[90:93]
	s_waitcnt lgkmcnt(0)
	v_mfma_f32_16x16x32_bf16 v[86:89], v[142:145], v[198:201], v[86:89]
	v_mfma_f32_16x16x32_bf16 v[74:77], v[150:153], v[198:201], v[74:77]
	s_setprio 0
	s_setprio 1
	v_mfma_f32_16x16x32_bf16 v[114:117], v[154:157], v[170:173], v[114:117]
	v_mfma_f32_16x16x32_bf16 v[110:113], v[162:165], v[170:173], v[110:113]
	v_mfma_f32_16x16x32_bf16 v[98:101], v[154:157], v[178:181], v[98:101]
	v_mfma_f32_16x16x32_bf16 v[94:97], v[162:165], v[178:181], v[94:97]
	v_mfma_f32_16x16x32_bf16 v[82:85], v[154:157], v[186:189], v[82:85]
	v_mfma_f32_16x16x32_bf16 v[78:81], v[162:165], v[186:189], v[78:81]
	v_mfma_f32_16x16x32_bf16 v[70:73], v[154:157], v[194:197], v[70:73]
	v_mfma_f32_16x16x32_bf16 v[66:69], v[162:165], v[194:197], v[66:69]
	v_mfma_f32_16x16x32_bf16 v[114:117], v[158:161], v[174:177], v[114:117]
	v_mfma_f32_16x16x32_bf16 v[110:113], v[166:169], v[174:177], v[110:113]
	v_mfma_f32_16x16x32_bf16 v[98:101], v[158:161], v[182:185], v[98:101]
	v_mfma_f32_16x16x32_bf16 v[94:97], v[166:169], v[182:185], v[94:97]
	v_mfma_f32_16x16x32_bf16 v[82:85], v[158:161], v[190:193], v[82:85]
	v_mfma_f32_16x16x32_bf16 v[78:81], v[166:169], v[190:193], v[78:81]
	v_mfma_f32_16x16x32_bf16 v[70:73], v[158:161], v[198:201], v[70:73]
	v_mfma_f32_16x16x32_bf16 v[66:69], v[166:169], v[198:201], v[66:69]
	s_setprio 0
	s_barrier
	ds_read_b128 v[170:173], v137 offset:49152
	ds_read_b128 v[174:177], v137 offset:50176
	s_add_i32 s57, s56, 0x80
	s_mov_b32 m0, s40
	s_nop 0
	buffer_load_dwordx4 v134, s[12:15], s57 offen lds
	ds_read_b128 v[178:181], v137 offset:51200
	ds_read_b128 v[182:185], v137 offset:52224
	s_add_i32 s56, s56, 0xb0080
	s_mov_b32 m0, s41
	s_nop 0
	buffer_load_dwordx4 v135, s[12:15], s57 offen lds
	ds_read_b128 v[186:189], v137 offset:53248
	ds_read_b128 v[190:193], v137 offset:54272
	s_nop 0
	s_mov_b32 m0, s44
	s_nop 0
	buffer_load_dwordx4 v134, s[12:15], s56 offen lds
	ds_read_b128 v[194:197], v137 offset:55296
	ds_read_b128 v[198:201], v137 offset:56320
	s_nop 0
	s_mov_b32 m0, s45
	s_nop 0
	buffer_load_dwordx4 v135, s[12:15], s56 offen lds
	s_nop 0
	s_mov_b32 m0, s42
	s_nop 0
	buffer_load_dwordx4 v134, s[16:19], s55 offen lds
	s_nop 0
	s_mov_b32 m0, s43
	s_nop 0
	buffer_load_dwordx4 v135, s[16:19], s55 offen lds
	s_waitcnt vmcnt(8)
	s_waitcnt lgkmcnt(0)
	s_barrier
	s_setprio 1
	s_waitcnt lgkmcnt(7)
	v_mfma_f32_16x16x32_bf16 v[62:65], v[138:141], v[170:173], v[62:65]
	v_mfma_f32_16x16x32_bf16 v[58:61], v[146:149], v[170:173], v[58:61]
	s_waitcnt lgkmcnt(5)
	v_mfma_f32_16x16x32_bf16 v[54:57], v[138:141], v[178:181], v[54:57]
	v_mfma_f32_16x16x32_bf16 v[42:45], v[146:149], v[178:181], v[42:45]
	s_waitcnt lgkmcnt(3)
	v_mfma_f32_16x16x32_bf16 v[38:41], v[138:141], v[186:189], v[38:41]
	v_mfma_f32_16x16x32_bf16 v[26:29], v[146:149], v[186:189], v[26:29]
	s_waitcnt lgkmcnt(1)
	v_mfma_f32_16x16x32_bf16 v[18:21], v[138:141], v[194:197], v[18:21]
	v_mfma_f32_16x16x32_bf16 v[10:13], v[146:149], v[194:197], v[10:13]
	v_mfma_f32_16x16x32_bf16 v[62:65], v[142:145], v[174:177], v[62:65]
	v_mfma_f32_16x16x32_bf16 v[58:61], v[150:153], v[174:177], v[58:61]
	v_mfma_f32_16x16x32_bf16 v[54:57], v[142:145], v[182:185], v[54:57]
	v_mfma_f32_16x16x32_bf16 v[42:45], v[150:153], v[182:185], v[42:45]
	v_mfma_f32_16x16x32_bf16 v[38:41], v[142:145], v[190:193], v[38:41]
	v_mfma_f32_16x16x32_bf16 v[26:29], v[150:153], v[190:193], v[26:29]
	s_waitcnt lgkmcnt(0)
	v_mfma_f32_16x16x32_bf16 v[18:21], v[142:145], v[198:201], v[18:21]
	v_mfma_f32_16x16x32_bf16 v[10:13], v[150:153], v[198:201], v[10:13]
	s_setprio 0
	s_setprio 1
	v_mfma_f32_16x16x32_bf16 v[50:53], v[154:157], v[170:173], v[50:53]
	v_mfma_f32_16x16x32_bf16 v[46:49], v[162:165], v[170:173], v[46:49]
	v_mfma_f32_16x16x32_bf16 v[34:37], v[154:157], v[178:181], v[34:37]
	v_mfma_f32_16x16x32_bf16 v[30:33], v[162:165], v[178:181], v[30:33]
	v_mfma_f32_16x16x32_bf16 v[22:25], v[154:157], v[186:189], v[22:25]
	v_mfma_f32_16x16x32_bf16 v[14:17], v[162:165], v[186:189], v[14:17]
	v_mfma_f32_16x16x32_bf16 v[6:9], v[154:157], v[194:197], v[6:9]
	v_mfma_f32_16x16x32_bf16 v[2:5], v[162:165], v[194:197], v[2:5]
	v_mfma_f32_16x16x32_bf16 v[50:53], v[158:161], v[174:177], v[50:53]
	v_mfma_f32_16x16x32_bf16 v[46:49], v[166:169], v[174:177], v[46:49]
	v_mfma_f32_16x16x32_bf16 v[34:37], v[158:161], v[182:185], v[34:37]
	v_mfma_f32_16x16x32_bf16 v[30:33], v[166:169], v[182:185], v[30:33]
	v_mfma_f32_16x16x32_bf16 v[22:25], v[158:161], v[190:193], v[22:25]
	v_mfma_f32_16x16x32_bf16 v[14:17], v[166:169], v[190:193], v[14:17]
	v_mfma_f32_16x16x32_bf16 v[6:9], v[158:161], v[198:201], v[6:9]
	v_mfma_f32_16x16x32_bf16 v[2:5], v[166:169], v[198:201], v[2:5]
	s_setprio 0
	s_add_i32 s2, s2, 2
	s_addk_i32 s3, 0x100
	s_cmp_gt_u32 s2, 41
	s_barrier
	s_cbranch_scc0 .LBB0_1135
	s_andn2_b64 vcc, exec, s[4:5]
	s_cbranch_vccnz .LBB0_1123
	v_mov_b32_e32 v2, 0
	s_mov_b32 s20, s50
	s_mov_b32 s25, s51
	s_mov_b32 s30, s54
	s_mov_b32 s36, s53
	s_mov_b32 s49, s52
	v_mov_b32_e32 v3, v2
	v_mov_b32_e32 v4, v2
	v_mov_b32_e32 v5, v2
	v_mov_b32_e32 v6, v2
	v_mov_b32_e32 v7, v2
	v_mov_b32_e32 v8, v2
	v_mov_b32_e32 v9, v2
	v_mov_b32_e32 v14, v2
	v_mov_b32_e32 v15, v2
	v_mov_b32_e32 v16, v2
	v_mov_b32_e32 v17, v2
	v_mov_b32_e32 v22, v2
	v_mov_b32_e32 v23, v2
	v_mov_b32_e32 v24, v2
	v_mov_b32_e32 v25, v2
	v_mov_b32_e32 v30, v2
	v_mov_b32_e32 v31, v2
	v_mov_b32_e32 v32, v2
	v_mov_b32_e32 v33, v2
	v_mov_b32_e32 v34, v2
	v_mov_b32_e32 v35, v2
	v_mov_b32_e32 v36, v2
	v_mov_b32_e32 v37, v2
	v_mov_b32_e32 v46, v2
	v_mov_b32_e32 v47, v2
	v_mov_b32_e32 v48, v2
	v_mov_b32_e32 v49, v2
	v_mov_b32_e32 v50, v2
	v_mov_b32_e32 v51, v2
	v_mov_b32_e32 v52, v2
	v_mov_b32_e32 v53, v2
	v_mov_b32_e32 v10, v2
	v_mov_b32_e32 v11, v2
	v_mov_b32_e32 v12, v2
	v_mov_b32_e32 v13, v2
	v_mov_b32_e32 v18, v2
	v_mov_b32_e32 v19, v2
	v_mov_b32_e32 v20, v2
	v_mov_b32_e32 v21, v2
	v_mov_b32_e32 v26, v2
	v_mov_b32_e32 v27, v2
	v_mov_b32_e32 v28, v2
	v_mov_b32_e32 v29, v2
	v_mov_b32_e32 v38, v2
	v_mov_b32_e32 v39, v2
	v_mov_b32_e32 v40, v2
	v_mov_b32_e32 v41, v2
	v_mov_b32_e32 v42, v2
	v_mov_b32_e32 v43, v2
	v_mov_b32_e32 v44, v2
	v_mov_b32_e32 v45, v2
	v_mov_b32_e32 v54, v2
	v_mov_b32_e32 v55, v2
	v_mov_b32_e32 v56, v2
	v_mov_b32_e32 v57, v2
	v_mov_b32_e32 v58, v2
	v_mov_b32_e32 v59, v2
	v_mov_b32_e32 v60, v2
	v_mov_b32_e32 v61, v2
	v_mov_b32_e32 v62, v2
	v_mov_b32_e32 v63, v2
	v_mov_b32_e32 v64, v2
	v_mov_b32_e32 v65, v2
	v_mov_b32_e32 v66, v2
	v_mov_b32_e32 v67, v2
	v_mov_b32_e32 v68, v2
	v_mov_b32_e32 v69, v2
	v_mov_b32_e32 v70, v2
	v_mov_b32_e32 v71, v2
	v_mov_b32_e32 v72, v2
	v_mov_b32_e32 v73, v2
	v_mov_b32_e32 v78, v2
	v_mov_b32_e32 v79, v2
	v_mov_b32_e32 v80, v2
	v_mov_b32_e32 v81, v2
	v_mov_b32_e32 v82, v2
	v_mov_b32_e32 v83, v2
	v_mov_b32_e32 v84, v2
	v_mov_b32_e32 v85, v2
	v_mov_b32_e32 v94, v2
	v_mov_b32_e32 v95, v2
	v_mov_b32_e32 v96, v2
	v_mov_b32_e32 v97, v2
	v_mov_b32_e32 v98, v2
	v_mov_b32_e32 v99, v2
	v_mov_b32_e32 v100, v2
	v_mov_b32_e32 v101, v2
	v_mov_b32_e32 v110, v2
	v_mov_b32_e32 v111, v2
	v_mov_b32_e32 v112, v2
	v_mov_b32_e32 v113, v2
	v_mov_b32_e32 v114, v2
	v_mov_b32_e32 v115, v2
	v_mov_b32_e32 v116, v2
	v_mov_b32_e32 v117, v2
	v_mov_b32_e32 v74, v2
	v_mov_b32_e32 v75, v2
	v_mov_b32_e32 v76, v2
	v_mov_b32_e32 v77, v2
	v_mov_b32_e32 v86, v2
	v_mov_b32_e32 v87, v2
	v_mov_b32_e32 v88, v2
	v_mov_b32_e32 v89, v2
	v_mov_b32_e32 v90, v2
	v_mov_b32_e32 v91, v2
	v_mov_b32_e32 v92, v2
	v_mov_b32_e32 v93, v2
	v_mov_b32_e32 v102, v2
	v_mov_b32_e32 v103, v2
	v_mov_b32_e32 v104, v2
	v_mov_b32_e32 v105, v2
	v_mov_b32_e32 v106, v2
	v_mov_b32_e32 v107, v2
	v_mov_b32_e32 v108, v2
	v_mov_b32_e32 v109, v2
	v_mov_b32_e32 v118, v2
	v_mov_b32_e32 v119, v2
	v_mov_b32_e32 v120, v2
	v_mov_b32_e32 v121, v2
	v_mov_b32_e32 v122, v2
	v_mov_b32_e32 v123, v2
	v_mov_b32_e32 v124, v2
	v_mov_b32_e32 v125, v2
	v_mov_b32_e32 v126, v2
	v_mov_b32_e32 v127, v2
	v_mov_b32_e32 v128, v2
	v_mov_b32_e32 v129, v2
	s_branch .LBB0_1123
